# k19
# speedup vs baseline: 1.1295x; 1.0050x over previous
.Lat_item:
	s_lshr_b32 s13, s22, 7
	s_lshr_b32 s20, s13, 1
	s_and_b32 s20, s20, 1
	s_xor_b32 s13, s13, s20
	s_sub_u32 s13, 15, s13
	s_and_b32 s14, s22, 0x7f
	s_lshr_b32 s15, s14, 3
	s_and_b32 s14, s14, 7
	s_lshl_b32 s16, s13, 7
	s_lshl_b32 s17, s13, 1
	s_add_u32 s17, s17, 2
	s_lshl_b32 s19, s15, 11
	s_add_u32 s19, s19, s16
	s_lshl_b32 s20, s19, 11
	s_lshl_b32 s21, s14, 8
	s_add_u32 s20, s20, s21
	s_add_u32 s76, s92, 0x16100000
	s_addc_u32 s77, s93, 0
	s_add_u32 s76, s76, s20
	s_addc_u32 s77, s77, 0
	global_load_dwordx4 a[0:3], v31, s[76:77] offset:0
	global_load_dwordx4 a[4:7], v31, s[76:77] offset:32
	global_load_dwordx4 a[8:11], v31, s[76:77] offset:64
	global_load_dwordx4 a[12:15], v31, s[76:77] offset:96
	global_load_dwordx4 a[16:19], v31, s[76:77] offset:128
	global_load_dwordx4 a[20:23], v31, s[76:77] offset:160
	global_load_dwordx4 a[24:27], v31, s[76:77] offset:192
	global_load_dwordx4 a[28:31], v31, s[76:77] offset:224
	s_lshl_b32 s20, s15, 22
	s_add_u32 s20, s20, s21
	s_add_u32 s78, s92, 0x1a100000
	s_addc_u32 s79, s93, 0
	s_add_u32 s78, s78, s20
	s_addc_u32 s79, s79, 0
	s_lshl_b32 s20, s15, 3
	s_add_u32 s20, s20, s14
	s_lshl_b32 s20, s20, 19
	s_add_u32 s80, s92, 0x1e100000
	s_addc_u32 s81, s93, 0
	s_add_u32 s80, s80, s20
	s_addc_u32 s81, s81, 0
	global_load_dwordx4 a[224:227], v8, s[78:79]
	global_load_dwordx4 a[228:231], v9, s[78:79]
	global_load_dwordx4 a[232:235], v10, s[78:79]
	global_load_dwordx4 a[236:239], v11, s[78:79]
	global_load_dwordx4 a[240:243], v12, s[80:81]
	global_load_dwordx4 a[244:247], v13, s[80:81]
	global_load_dwordx4 a[248:251], v14, s[80:81]
	global_load_dwordx4 a[252:255], v15, s[80:81]
	v_mov_b32_e32 v64, 0
	v_mov_b32_e32 v65, 0
	v_mov_b32_e32 v66, 0
	v_mov_b32_e32 v67, 0
	v_mov_b32_e32 v68, 0
	v_mov_b32_e32 v69, 0
	v_mov_b32_e32 v70, 0
	v_mov_b32_e32 v71, 0
	v_mov_b32_e32 v72, 0
	v_mov_b32_e32 v73, 0
	v_mov_b32_e32 v74, 0
	v_mov_b32_e32 v75, 0
	v_mov_b32_e32 v76, 0
	v_mov_b32_e32 v77, 0
	v_mov_b32_e32 v78, 0
	v_mov_b32_e32 v79, 0
	v_mov_b32_e32 v80, 0
	v_mov_b32_e32 v81, 0
	v_mov_b32_e32 v82, 0
	v_mov_b32_e32 v83, 0
	v_mov_b32_e32 v84, 0
	v_mov_b32_e32 v85, 0
	v_mov_b32_e32 v86, 0
	v_mov_b32_e32 v87, 0
	v_mov_b32_e32 v88, 0
	v_mov_b32_e32 v89, 0
	v_mov_b32_e32 v90, 0
	v_mov_b32_e32 v91, 0
	v_mov_b32_e32 v92, 0
	v_mov_b32_e32 v93, 0
	v_mov_b32_e32 v94, 0
	v_mov_b32_e32 v95, 0
	v_mov_b32_e32 v96, 0
	v_mov_b32_e32 v97, 0
	v_mov_b32_e32 v98, 0
	v_mov_b32_e32 v99, 0
	v_mov_b32_e32 v100, 0
	v_mov_b32_e32 v101, 0
	v_mov_b32_e32 v102, 0
	v_mov_b32_e32 v103, 0
	v_mov_b32_e32 v104, 0
	v_mov_b32_e32 v105, 0
	v_mov_b32_e32 v106, 0
	v_mov_b32_e32 v107, 0
	v_mov_b32_e32 v108, 0
	v_mov_b32_e32 v109, 0
	v_mov_b32_e32 v110, 0
	v_mov_b32_e32 v111, 0
	v_mov_b32_e32 v112, 0
	v_mov_b32_e32 v113, 0
	v_mov_b32_e32 v114, 0
	v_mov_b32_e32 v115, 0
	v_mov_b32_e32 v116, 0
	v_mov_b32_e32 v117, 0
	v_mov_b32_e32 v118, 0
	v_mov_b32_e32 v119, 0
	v_mov_b32_e32 v120, 0
	v_mov_b32_e32 v121, 0
	v_mov_b32_e32 v122, 0
	v_mov_b32_e32 v123, 0
	v_mov_b32_e32 v124, 0
	v_mov_b32_e32 v125, 0
	v_mov_b32_e32 v126, 0
	v_mov_b32_e32 v127, 0
	v_mov_b32_e32 v128, 0
	v_mov_b32_e32 v129, 0
	v_mov_b32_e32 v130, 0
	v_mov_b32_e32 v131, 0
	v_mov_b32_e32 v132, 0
	v_mov_b32_e32 v133, 0
	v_mov_b32_e32 v134, 0
	v_mov_b32_e32 v135, 0
	v_mov_b32_e32 v136, 0
	v_mov_b32_e32 v137, 0
	v_mov_b32_e32 v138, 0
	v_mov_b32_e32 v139, 0
	v_mov_b32_e32 v140, 0
	v_mov_b32_e32 v141, 0
	v_mov_b32_e32 v142, 0
	v_mov_b32_e32 v143, 0
	v_mov_b32_e32 v144, 0
	v_mov_b32_e32 v145, 0
	v_mov_b32_e32 v146, 0
	v_mov_b32_e32 v147, 0
	v_mov_b32_e32 v148, 0
	v_mov_b32_e32 v149, 0
	v_mov_b32_e32 v150, 0
	v_mov_b32_e32 v151, 0
	v_mov_b32_e32 v152, 0
	v_mov_b32_e32 v153, 0
	v_mov_b32_e32 v154, 0
	v_mov_b32_e32 v155, 0
	v_mov_b32_e32 v156, 0
	v_mov_b32_e32 v157, 0
	v_mov_b32_e32 v158, 0
	v_mov_b32_e32 v159, 0
	v_mov_b32_e32 v160, 0
	v_mov_b32_e32 v161, 0
	v_mov_b32_e32 v162, 0
	v_mov_b32_e32 v163, 0
	v_mov_b32_e32 v164, 0
	v_mov_b32_e32 v165, 0
	v_mov_b32_e32 v166, 0
	v_mov_b32_e32 v167, 0
	v_mov_b32_e32 v168, 0
	v_mov_b32_e32 v169, 0
	v_mov_b32_e32 v170, 0
	v_mov_b32_e32 v171, 0
	v_mov_b32_e32 v172, 0
	v_mov_b32_e32 v173, 0
	v_mov_b32_e32 v174, 0
	v_mov_b32_e32 v175, 0
	v_mov_b32_e32 v176, 0
	v_mov_b32_e32 v177, 0
	v_mov_b32_e32 v178, 0
	v_mov_b32_e32 v179, 0
	v_mov_b32_e32 v180, 0
	v_mov_b32_e32 v181, 0
	v_mov_b32_e32 v182, 0
	v_mov_b32_e32 v183, 0
	v_mov_b32_e32 v184, 0
	v_mov_b32_e32 v185, 0
	v_mov_b32_e32 v186, 0
	v_mov_b32_e32 v187, 0
	v_mov_b32_e32 v188, 0
	v_mov_b32_e32 v189, 0
	v_mov_b32_e32 v190, 0
	v_mov_b32_e32 v191, 0
	v_mov_b32_e32 v20, v27
	v_mov_b32_e32 v21, v27
	v_mov_b32_e32 v22, 0
	v_mov_b32_e32 v23, 0
	v_add_u32_e32 v25, s16, v30
	v_lshlrev_b32_e32 v28, 2, v2
	v_sub_u32_e32 v25, v25, v28
	s_lshl_b32 s84, s7, 5
	s_add_u32 s84, s84, s16
	s_mov_b32 s85, 0
	s_mov_b32 s86, 0
	s_mov_b32 s87, 0
	s_barrier
	s_waitcnt vmcnt(0)
	ds_write_b128 v16, a[224:227] offset:0
	ds_write_b128 v16, a[228:231] offset:4352
	ds_write_b128 v16, a[232:235] offset:8704
	ds_write_b128 v16, a[236:239] offset:13056
	ds_write_b128 v18, a[240:243] offset:0
	ds_write_b128 v18, a[244:247] offset:4608
	ds_write_b128 v18, a[248:251] offset:9216
	ds_write_b128 v18, a[252:255] offset:13824
	s_waitcnt lgkmcnt(0)
	s_barrier

.Lgu_loop:
	s_waitcnt vmcnt(20)
	v_mov_b32_e32 v8, v10
	v_mov_b32_e32 v9, v11
	ds_bpermute_b32 v192, v4, v8
	ds_bpermute_b32 v193, v4, v8 offset:32
	ds_bpermute_b32 v194, v4, v8 offset:64
	ds_bpermute_b32 v195, v4, v8 offset:96
	ds_bpermute_b32 v196, v4, v8 offset:128
	ds_bpermute_b32 v197, v4, v8 offset:160
	ds_bpermute_b32 v198, v4, v8 offset:192
	ds_bpermute_b32 v199, v4, v8 offset:224
	ds_bpermute_b32 v200, v4, v9
	ds_bpermute_b32 v201, v4, v9 offset:32
	ds_bpermute_b32 v202, v4, v9 offset:64
	ds_bpermute_b32 v203, v4, v9 offset:96
	ds_bpermute_b32 v204, v4, v9 offset:128
	ds_bpermute_b32 v205, v4, v9 offset:160
	ds_bpermute_b32 v206, v4, v9 offset:192
	ds_bpermute_b32 v207, v4, v9 offset:224
	s_mov_b32 s31, s12
	s_add_u32 s26, s22, s31
	s_min_u32 s26, s26, 0x7fff
	s_mov_b32 s42, s26
	s_mul_i32 s31, s12, 2
	s_add_u32 s26, s22, s31
	s_min_u32 s26, s26, 0x7fff
	s_lshl_b32 s30, s26, 9
	s_add_u32 s40, s18, s30
	s_addc_u32 s41, s19, 0
	global_load_dword v10, v1, s[40:41]
	global_load_dword v11, v1, s[40:41] offset:256
	s_waitcnt lgkmcnt(0)
	s_lshl_b32 s30, s42, 12
	s_add_u32 s66, s16, s30
	s_addc_u32 s67, s17, 0
	global_load_dwordx4 v[224:227], v7, s[66:67]
	global_load_dwordx4 v[228:231], v7, s[66:67] offset:16
	global_load_dwordx4 v[232:235], v7, s[66:67] offset:32
	global_load_dwordx4 v[236:239], v7, s[66:67] offset:48
	v_lshl_add_u32 v192, v192, 7, v3
	global_load_dwordx4 v[128:131], v192, s[14:15]
	v_lshl_add_u32 v193, v193, 7, v3
	global_load_dwordx4 v[132:135], v193, s[14:15]
	v_lshl_add_u32 v194, v194, 7, v3
	global_load_dwordx4 v[136:139], v194, s[14:15]
	v_lshl_add_u32 v195, v195, 7, v3
	global_load_dwordx4 v[140:143], v195, s[14:15]
	v_lshl_add_u32 v196, v196, 7, v3
	global_load_dwordx4 v[144:147], v196, s[14:15]
	v_lshl_add_u32 v197, v197, 7, v3
	global_load_dwordx4 v[148:151], v197, s[14:15]
	v_lshl_add_u32 v198, v198, 7, v3
	global_load_dwordx4 v[152:155], v198, s[14:15]
	v_lshl_add_u32 v199, v199, 7, v3
	global_load_dwordx4 v[156:159], v199, s[14:15]
	v_lshl_add_u32 v200, v200, 7, v3
	global_load_dwordx4 v[160:163], v200, s[14:15]
	v_lshl_add_u32 v201, v201, 7, v3
	global_load_dwordx4 v[164:167], v201, s[14:15]
	v_lshl_add_u32 v202, v202, 7, v3
	global_load_dwordx4 v[168:171], v202, s[14:15]
	v_lshl_add_u32 v203, v203, 7, v3
	global_load_dwordx4 v[172:175], v203, s[14:15]
	v_lshl_add_u32 v204, v204, 7, v3
	global_load_dwordx4 v[176:179], v204, s[14:15]
	v_lshl_add_u32 v205, v205, 7, v3
	global_load_dwordx4 v[180:183], v205, s[14:15]
	v_lshl_add_u32 v206, v206, 7, v3
	global_load_dwordx4 v[184:187], v206, s[14:15]
	v_lshl_add_u32 v207, v207, 7, v3
	global_load_dwordx4 v[188:191], v207, s[14:15]
	s_waitcnt vmcnt(22)
	v_cvt_pk_f32_fp8_e32 v[40:41], v64
	v_cvt_pk_f32_fp8_sdwa v[42:43], v64 src0_sel:WORD_1
	v_cvt_pk_f32_fp8_e32 v[44:45], v65
	v_cvt_pk_f32_fp8_sdwa v[46:47], v65 src0_sel:WORD_1
	v_cvt_pk_f32_fp8_e32 v[48:49], v66
	v_cvt_pk_f32_fp8_sdwa v[50:51], v66 src0_sel:WORD_1
	v_cvt_pk_f32_fp8_e32 v[52:53], v67
	v_cvt_pk_f32_fp8_sdwa v[54:55], v67 src0_sel:WORD_1
	v_pk_mul_f32 v[24:25], v[40:41], v[208:209]
	v_pk_fma_f32 v[24:25], v[42:43], v[210:211], v[24:25]
	v_pk_fma_f32 v[24:25], v[44:45], v[212:213], v[24:25]
	v_pk_fma_f32 v[24:25], v[46:47], v[214:215], v[24:25]
	v_pk_fma_f32 v[24:25], v[48:49], v[216:217], v[24:25]
	v_pk_fma_f32 v[24:25], v[50:51], v[218:219], v[24:25]
	v_pk_fma_f32 v[24:25], v[52:53], v[220:221], v[24:25]
	v_pk_fma_f32 v[24:25], v[54:55], v[222:223], v[24:25]
	v_add_f32_e32 v56, v24, v25
	ds_write_b32 v5, v56
	v_cvt_pk_f32_fp8_e32 v[40:41], v68
	v_cvt_pk_f32_fp8_sdwa v[42:43], v68 src0_sel:WORD_1
	v_cvt_pk_f32_fp8_e32 v[44:45], v69
	v_cvt_pk_f32_fp8_sdwa v[46:47], v69 src0_sel:WORD_1
	v_cvt_pk_f32_fp8_e32 v[48:49], v70
	v_cvt_pk_f32_fp8_sdwa v[50:51], v70 src0_sel:WORD_1
	v_cvt_pk_f32_fp8_e32 v[52:53], v71
	v_cvt_pk_f32_fp8_sdwa v[54:55], v71 src0_sel:WORD_1
	v_pk_mul_f32 v[24:25], v[40:41], v[208:209]
	v_pk_fma_f32 v[24:25], v[42:43], v[210:211], v[24:25]
	v_pk_fma_f32 v[24:25], v[44:45], v[212:213], v[24:25]
	v_pk_fma_f32 v[24:25], v[46:47], v[214:215], v[24:25]
	v_pk_fma_f32 v[24:25], v[48:49], v[216:217], v[24:25]
	v_pk_fma_f32 v[24:25], v[50:51], v[218:219], v[24:25]
	v_pk_fma_f32 v[24:25], v[52:53], v[220:221], v[24:25]
	v_pk_fma_f32 v[24:25], v[54:55], v[222:223], v[24:25]
	v_add_f32_e32 v56, v24, v25
	ds_write_b32 v5, v56 offset:256
	v_cvt_pk_f32_fp8_e32 v[40:41], v72
	v_cvt_pk_f32_fp8_sdwa v[42:43], v72 src0_sel:WORD_1
	v_cvt_pk_f32_fp8_e32 v[44:45], v73
	v_cvt_pk_f32_fp8_sdwa v[46:47], v73 src0_sel:WORD_1
	v_cvt_pk_f32_fp8_e32 v[48:49], v74
	v_cvt_pk_f32_fp8_sdwa v[50:51], v74 src0_sel:WORD_1
	v_cvt_pk_f32_fp8_e32 v[52:53], v75
	v_cvt_pk_f32_fp8_sdwa v[54:55], v75 src0_sel:WORD_1
	v_pk_mul_f32 v[24:25], v[40:41], v[208:209]
	v_pk_fma_f32 v[24:25], v[42:43], v[210:211], v[24:25]
	v_pk_fma_f32 v[24:25], v[44:45], v[212:213], v[24:25]
	v_pk_fma_f32 v[24:25], v[46:47], v[214:215], v[24:25]
	v_pk_fma_f32 v[24:25], v[48:49], v[216:217], v[24:25]
	v_pk_fma_f32 v[24:25], v[50:51], v[218:219], v[24:25]
	v_pk_fma_f32 v[24:25], v[52:53], v[220:221], v[24:25]
	v_pk_fma_f32 v[24:25], v[54:55], v[222:223], v[24:25]
	v_add_f32_e32 v56, v24, v25
	ds_write_b32 v5, v56 offset:512
	v_cvt_pk_f32_fp8_e32 v[40:41], v76
	v_cvt_pk_f32_fp8_sdwa v[42:43], v76 src0_sel:WORD_1
	v_cvt_pk_f32_fp8_e32 v[44:45], v77
	v_cvt_pk_f32_fp8_sdwa v[46:47], v77 src0_sel:WORD_1
	v_cvt_pk_f32_fp8_e32 v[48:49], v78
	v_cvt_pk_f32_fp8_sdwa v[50:51], v78 src0_sel:WORD_1
	v_cvt_pk_f32_fp8_e32 v[52:53], v79
	v_cvt_pk_f32_fp8_sdwa v[54:55], v79 src0_sel:WORD_1
	v_pk_mul_f32 v[24:25], v[40:41], v[208:209]
	v_pk_fma_f32 v[24:25], v[42:43], v[210:211], v[24:25]
	v_pk_fma_f32 v[24:25], v[44:45], v[212:213], v[24:25]
	v_pk_fma_f32 v[24:25], v[46:47], v[214:215], v[24:25]
	v_pk_fma_f32 v[24:25], v[48:49], v[216:217], v[24:25]
	v_pk_fma_f32 v[24:25], v[50:51], v[218:219], v[24:25]
	v_pk_fma_f32 v[24:25], v[52:53], v[220:221], v[24:25]
	v_pk_fma_f32 v[24:25], v[54:55], v[222:223], v[24:25]
	v_add_f32_e32 v56, v24, v25
	ds_write_b32 v5, v56 offset:768
	v_cvt_pk_f32_fp8_e32 v[40:41], v80
	v_cvt_pk_f32_fp8_sdwa v[42:43], v80 src0_sel:WORD_1
	v_cvt_pk_f32_fp8_e32 v[44:45], v81
	v_cvt_pk_f32_fp8_sdwa v[46:47], v81 src0_sel:WORD_1
	v_cvt_pk_f32_fp8_e32 v[48:49], v82
	v_cvt_pk_f32_fp8_sdwa v[50:51], v82 src0_sel:WORD_1
	v_cvt_pk_f32_fp8_e32 v[52:53], v83
	v_cvt_pk_f32_fp8_sdwa v[54:55], v83 src0_sel:WORD_1
	v_pk_mul_f32 v[24:25], v[40:41], v[208:209]
	v_pk_fma_f32 v[24:25], v[42:43], v[210:211], v[24:25]
	v_pk_fma_f32 v[24:25], v[44:45], v[212:213], v[24:25]
	v_pk_fma_f32 v[24:25], v[46:47], v[214:215], v[24:25]
	v_pk_fma_f32 v[24:25], v[48:49], v[216:217], v[24:25]
	v_pk_fma_f32 v[24:25], v[50:51], v[218:219], v[24:25]
	v_pk_fma_f32 v[24:25], v[52:53], v[220:221], v[24:25]
	v_pk_fma_f32 v[24:25], v[54:55], v[222:223], v[24:25]
	v_add_f32_e32 v56, v24, v25
	ds_write_b32 v5, v56 offset:1024
	v_cvt_pk_f32_fp8_e32 v[40:41], v84
	v_cvt_pk_f32_fp8_sdwa v[42:43], v84 src0_sel:WORD_1
	v_cvt_pk_f32_fp8_e32 v[44:45], v85
	v_cvt_pk_f32_fp8_sdwa v[46:47], v85 src0_sel:WORD_1
	v_cvt_pk_f32_fp8_e32 v[48:49], v86
	v_cvt_pk_f32_fp8_sdwa v[50:51], v86 src0_sel:WORD_1
	v_cvt_pk_f32_fp8_e32 v[52:53], v87
	v_cvt_pk_f32_fp8_sdwa v[54:55], v87 src0_sel:WORD_1
	v_pk_mul_f32 v[24:25], v[40:41], v[208:209]
	v_pk_fma_f32 v[24:25], v[42:43], v[210:211], v[24:25]
	v_pk_fma_f32 v[24:25], v[44:45], v[212:213], v[24:25]
	v_pk_fma_f32 v[24:25], v[46:47], v[214:215], v[24:25]
	v_pk_fma_f32 v[24:25], v[48:49], v[216:217], v[24:25]
	v_pk_fma_f32 v[24:25], v[50:51], v[218:219], v[24:25]
	v_pk_fma_f32 v[24:25], v[52:53], v[220:221], v[24:25]
	v_pk_fma_f32 v[24:25], v[54:55], v[222:223], v[24:25]
	v_add_f32_e32 v56, v24, v25
	ds_write_b32 v5, v56 offset:1280
	v_cvt_pk_f32_fp8_e32 v[40:41], v88
	v_cvt_pk_f32_fp8_sdwa v[42:43], v88 src0_sel:WORD_1
	v_cvt_pk_f32_fp8_e32 v[44:45], v89
	v_cvt_pk_f32_fp8_sdwa v[46:47], v89 src0_sel:WORD_1
	v_cvt_pk_f32_fp8_e32 v[48:49], v90
	v_cvt_pk_f32_fp8_sdwa v[50:51], v90 src0_sel:WORD_1
	v_cvt_pk_f32_fp8_e32 v[52:53], v91
	v_cvt_pk_f32_fp8_sdwa v[54:55], v91 src0_sel:WORD_1
	v_pk_mul_f32 v[24:25], v[40:41], v[208:209]
	v_pk_fma_f32 v[24:25], v[42:43], v[210:211], v[24:25]
	v_pk_fma_f32 v[24:25], v[44:45], v[212:213], v[24:25]
	v_pk_fma_f32 v[24:25], v[46:47], v[214:215], v[24:25]
	v_pk_fma_f32 v[24:25], v[48:49], v[216:217], v[24:25]
	v_pk_fma_f32 v[24:25], v[50:51], v[218:219], v[24:25]
	v_pk_fma_f32 v[24:25], v[52:53], v[220:221], v[24:25]
	v_pk_fma_f32 v[24:25], v[54:55], v[222:223], v[24:25]
	v_add_f32_e32 v56, v24, v25
	ds_write_b32 v5, v56 offset:1536
	v_cvt_pk_f32_fp8_e32 v[40:41], v92
	v_cvt_pk_f32_fp8_sdwa v[42:43], v92 src0_sel:WORD_1
	v_cvt_pk_f32_fp8_e32 v[44:45], v93
	v_cvt_pk_f32_fp8_sdwa v[46:47], v93 src0_sel:WORD_1
	v_cvt_pk_f32_fp8_e32 v[48:49], v94
	v_cvt_pk_f32_fp8_sdwa v[50:51], v94 src0_sel:WORD_1
	v_cvt_pk_f32_fp8_e32 v[52:53], v95
	v_cvt_pk_f32_fp8_sdwa v[54:55], v95 src0_sel:WORD_1
	v_pk_mul_f32 v[24:25], v[40:41], v[208:209]
	v_pk_fma_f32 v[24:25], v[42:43], v[210:211], v[24:25]
	v_pk_fma_f32 v[24:25], v[44:45], v[212:213], v[24:25]
	v_pk_fma_f32 v[24:25], v[46:47], v[214:215], v[24:25]
	v_pk_fma_f32 v[24:25], v[48:49], v[216:217], v[24:25]
	v_pk_fma_f32 v[24:25], v[50:51], v[218:219], v[24:25]
	v_pk_fma_f32 v[24:25], v[52:53], v[220:221], v[24:25]
	v_pk_fma_f32 v[24:25], v[54:55], v[222:223], v[24:25]
	v_add_f32_e32 v56, v24, v25
	ds_write_b32 v5, v56 offset:1792
	v_cvt_pk_f32_fp8_e32 v[40:41], v96
	v_cvt_pk_f32_fp8_sdwa v[42:43], v96 src0_sel:WORD_1
	v_cvt_pk_f32_fp8_e32 v[44:45], v97
	v_cvt_pk_f32_fp8_sdwa v[46:47], v97 src0_sel:WORD_1
	v_cvt_pk_f32_fp8_e32 v[48:49], v98
	v_cvt_pk_f32_fp8_sdwa v[50:51], v98 src0_sel:WORD_1
	v_cvt_pk_f32_fp8_e32 v[52:53], v99
	v_cvt_pk_f32_fp8_sdwa v[54:55], v99 src0_sel:WORD_1
	v_pk_mul_f32 v[24:25], v[40:41], v[208:209]
	v_pk_fma_f32 v[24:25], v[42:43], v[210:211], v[24:25]
	v_pk_fma_f32 v[24:25], v[44:45], v[212:213], v[24:25]
	v_pk_fma_f32 v[24:25], v[46:47], v[214:215], v[24:25]
	v_pk_fma_f32 v[24:25], v[48:49], v[216:217], v[24:25]
	v_pk_fma_f32 v[24:25], v[50:51], v[218:219], v[24:25]
	v_pk_fma_f32 v[24:25], v[52:53], v[220:221], v[24:25]
	v_pk_fma_f32 v[24:25], v[54:55], v[222:223], v[24:25]
	v_add_f32_e32 v56, v24, v25
	ds_write_b32 v5, v56 offset:2048
	v_cvt_pk_f32_fp8_e32 v[40:41], v100
	v_cvt_pk_f32_fp8_sdwa v[42:43], v100 src0_sel:WORD_1
	v_cvt_pk_f32_fp8_e32 v[44:45], v101
	v_cvt_pk_f32_fp8_sdwa v[46:47], v101 src0_sel:WORD_1
	v_cvt_pk_f32_fp8_e32 v[48:49], v102
	v_cvt_pk_f32_fp8_sdwa v[50:51], v102 src0_sel:WORD_1
	v_cvt_pk_f32_fp8_e32 v[52:53], v103
	v_cvt_pk_f32_fp8_sdwa v[54:55], v103 src0_sel:WORD_1
	v_pk_mul_f32 v[24:25], v[40:41], v[208:209]
	v_pk_fma_f32 v[24:25], v[42:43], v[210:211], v[24:25]
	v_pk_fma_f32 v[24:25], v[44:45], v[212:213], v[24:25]
	v_pk_fma_f32 v[24:25], v[46:47], v[214:215], v[24:25]
	v_pk_fma_f32 v[24:25], v[48:49], v[216:217], v[24:25]
	v_pk_fma_f32 v[24:25], v[50:51], v[218:219], v[24:25]
	v_pk_fma_f32 v[24:25], v[52:53], v[220:221], v[24:25]
	v_pk_fma_f32 v[24:25], v[54:55], v[222:223], v[24:25]
	v_add_f32_e32 v56, v24, v25
	ds_write_b32 v5, v56 offset:2304
	v_cvt_pk_f32_fp8_e32 v[40:41], v104
	v_cvt_pk_f32_fp8_sdwa v[42:43], v104 src0_sel:WORD_1
	v_cvt_pk_f32_fp8_e32 v[44:45], v105
	v_cvt_pk_f32_fp8_sdwa v[46:47], v105 src0_sel:WORD_1
	v_cvt_pk_f32_fp8_e32 v[48:49], v106
	v_cvt_pk_f32_fp8_sdwa v[50:51], v106 src0_sel:WORD_1
	v_cvt_pk_f32_fp8_e32 v[52:53], v107
	v_cvt_pk_f32_fp8_sdwa v[54:55], v107 src0_sel:WORD_1
	v_pk_mul_f32 v[24:25], v[40:41], v[208:209]
	v_pk_fma_f32 v[24:25], v[42:43], v[210:211], v[24:25]
	v_pk_fma_f32 v[24:25], v[44:45], v[212:213], v[24:25]
	v_pk_fma_f32 v[24:25], v[46:47], v[214:215], v[24:25]
	v_pk_fma_f32 v[24:25], v[48:49], v[216:217], v[24:25]
	v_pk_fma_f32 v[24:25], v[50:51], v[218:219], v[24:25]
	v_pk_fma_f32 v[24:25], v[52:53], v[220:221], v[24:25]
	v_pk_fma_f32 v[24:25], v[54:55], v[222:223], v[24:25]
	v_add_f32_e32 v56, v24, v25
	ds_write_b32 v5, v56 offset:2560
	v_cvt_pk_f32_fp8_e32 v[40:41], v108
	v_cvt_pk_f32_fp8_sdwa v[42:43], v108 src0_sel:WORD_1
	v_cvt_pk_f32_fp8_e32 v[44:45], v109
	v_cvt_pk_f32_fp8_sdwa v[46:47], v109 src0_sel:WORD_1
	v_cvt_pk_f32_fp8_e32 v[48:49], v110
	v_cvt_pk_f32_fp8_sdwa v[50:51], v110 src0_sel:WORD_1
	v_cvt_pk_f32_fp8_e32 v[52:53], v111
	v_cvt_pk_f32_fp8_sdwa v[54:55], v111 src0_sel:WORD_1
	v_pk_mul_f32 v[24:25], v[40:41], v[208:209]
	v_pk_fma_f32 v[24:25], v[42:43], v[210:211], v[24:25]
	v_pk_fma_f32 v[24:25], v[44:45], v[212:213], v[24:25]
	v_pk_fma_f32 v[24:25], v[46:47], v[214:215], v[24:25]
	v_pk_fma_f32 v[24:25], v[48:49], v[216:217], v[24:25]
	v_pk_fma_f32 v[24:25], v[50:51], v[218:219], v[24:25]
	v_pk_fma_f32 v[24:25], v[52:53], v[220:221], v[24:25]
	v_pk_fma_f32 v[24:25], v[54:55], v[222:223], v[24:25]
	v_add_f32_e32 v56, v24, v25
	ds_write_b32 v5, v56 offset:2816
	v_cvt_pk_f32_fp8_e32 v[40:41], v112
	v_cvt_pk_f32_fp8_sdwa v[42:43], v112 src0_sel:WORD_1
	v_cvt_pk_f32_fp8_e32 v[44:45], v113
	v_cvt_pk_f32_fp8_sdwa v[46:47], v113 src0_sel:WORD_1
	v_cvt_pk_f32_fp8_e32 v[48:49], v114
	v_cvt_pk_f32_fp8_sdwa v[50:51], v114 src0_sel:WORD_1
	v_cvt_pk_f32_fp8_e32 v[52:53], v115
	v_cvt_pk_f32_fp8_sdwa v[54:55], v115 src0_sel:WORD_1
	v_pk_mul_f32 v[24:25], v[40:41], v[208:209]
	v_pk_fma_f32 v[24:25], v[42:43], v[210:211], v[24:25]
	v_pk_fma_f32 v[24:25], v[44:45], v[212:213], v[24:25]
	v_pk_fma_f32 v[24:25], v[46:47], v[214:215], v[24:25]
	v_pk_fma_f32 v[24:25], v[48:49], v[216:217], v[24:25]
	v_pk_fma_f32 v[24:25], v[50:51], v[218:219], v[24:25]
	v_pk_fma_f32 v[24:25], v[52:53], v[220:221], v[24:25]
	v_pk_fma_f32 v[24:25], v[54:55], v[222:223], v[24:25]
	v_add_f32_e32 v56, v24, v25
	ds_write_b32 v5, v56 offset:3072
	v_cvt_pk_f32_fp8_e32 v[40:41], v116
	v_cvt_pk_f32_fp8_sdwa v[42:43], v116 src0_sel:WORD_1
	v_cvt_pk_f32_fp8_e32 v[44:45], v117
	v_cvt_pk_f32_fp8_sdwa v[46:47], v117 src0_sel:WORD_1
	v_cvt_pk_f32_fp8_e32 v[48:49], v118
	v_cvt_pk_f32_fp8_sdwa v[50:51], v118 src0_sel:WORD_1
	v_cvt_pk_f32_fp8_e32 v[52:53], v119
	v_cvt_pk_f32_fp8_sdwa v[54:55], v119 src0_sel:WORD_1
	v_pk_mul_f32 v[24:25], v[40:41], v[208:209]
	v_pk_fma_f32 v[24:25], v[42:43], v[210:211], v[24:25]
	v_pk_fma_f32 v[24:25], v[44:45], v[212:213], v[24:25]
	v_pk_fma_f32 v[24:25], v[46:47], v[214:215], v[24:25]
	v_pk_fma_f32 v[24:25], v[48:49], v[216:217], v[24:25]
	v_pk_fma_f32 v[24:25], v[50:51], v[218:219], v[24:25]
	v_pk_fma_f32 v[24:25], v[52:53], v[220:221], v[24:25]
	v_pk_fma_f32 v[24:25], v[54:55], v[222:223], v[24:25]
	v_add_f32_e32 v56, v24, v25
	ds_write_b32 v5, v56 offset:3328
	v_cvt_pk_f32_fp8_e32 v[40:41], v120
	v_cvt_pk_f32_fp8_sdwa v[42:43], v120 src0_sel:WORD_1
	v_cvt_pk_f32_fp8_e32 v[44:45], v121
	v_cvt_pk_f32_fp8_sdwa v[46:47], v121 src0_sel:WORD_1
	v_cvt_pk_f32_fp8_e32 v[48:49], v122
	v_cvt_pk_f32_fp8_sdwa v[50:51], v122 src0_sel:WORD_1
	v_cvt_pk_f32_fp8_e32 v[52:53], v123
	v_cvt_pk_f32_fp8_sdwa v[54:55], v123 src0_sel:WORD_1
	v_pk_mul_f32 v[24:25], v[40:41], v[208:209]
	v_pk_fma_f32 v[24:25], v[42:43], v[210:211], v[24:25]
	v_pk_fma_f32 v[24:25], v[44:45], v[212:213], v[24:25]
	v_pk_fma_f32 v[24:25], v[46:47], v[214:215], v[24:25]
	v_pk_fma_f32 v[24:25], v[48:49], v[216:217], v[24:25]
	v_pk_fma_f32 v[24:25], v[50:51], v[218:219], v[24:25]
	v_pk_fma_f32 v[24:25], v[52:53], v[220:221], v[24:25]
	v_pk_fma_f32 v[24:25], v[54:55], v[222:223], v[24:25]
	v_add_f32_e32 v56, v24, v25
	ds_write_b32 v5, v56 offset:3584
	v_cvt_pk_f32_fp8_e32 v[40:41], v124
	v_cvt_pk_f32_fp8_sdwa v[42:43], v124 src0_sel:WORD_1
	v_cvt_pk_f32_fp8_e32 v[44:45], v125
	v_cvt_pk_f32_fp8_sdwa v[46:47], v125 src0_sel:WORD_1
	v_cvt_pk_f32_fp8_e32 v[48:49], v126
	v_cvt_pk_f32_fp8_sdwa v[50:51], v126 src0_sel:WORD_1
	v_cvt_pk_f32_fp8_e32 v[52:53], v127
	v_cvt_pk_f32_fp8_sdwa v[54:55], v127 src0_sel:WORD_1
	v_pk_mul_f32 v[24:25], v[40:41], v[208:209]
	v_pk_fma_f32 v[24:25], v[42:43], v[210:211], v[24:25]
	v_pk_fma_f32 v[24:25], v[44:45], v[212:213], v[24:25]
	v_pk_fma_f32 v[24:25], v[46:47], v[214:215], v[24:25]
	v_pk_fma_f32 v[24:25], v[48:49], v[216:217], v[24:25]
	v_pk_fma_f32 v[24:25], v[50:51], v[218:219], v[24:25]
	v_pk_fma_f32 v[24:25], v[52:53], v[220:221], v[24:25]
	v_pk_fma_f32 v[24:25], v[54:55], v[222:223], v[24:25]
	v_add_f32_e32 v56, v24, v25
	ds_write_b32 v5, v56 offset:3840
	ds_read_b128 v[40:43], v6
	ds_read_b128 v[44:47], v6 offset:16
	ds_read_b128 v[48:51], v6 offset:2048
	ds_read_b128 v[52:55], v6 offset:2064
	s_waitcnt lgkmcnt(2)
	v_add_f32_e32 v40, v40, v41
	v_add_f32_e32 v40, v40, v42
	v_add_f32_e32 v40, v40, v43
	v_add_f32_e32 v40, v40, v44
	v_add_f32_e32 v40, v40, v45
	v_add_f32_e32 v40, v40, v46
	v_add_f32_e32 v40, v40, v47
	s_waitcnt lgkmcnt(0)
	v_add_f32_e32 v48, v48, v49
	v_add_f32_e32 v48, v48, v50
	v_add_f32_e32 v48, v48, v51
	v_add_f32_e32 v48, v48, v52
	v_add_f32_e32 v48, v48, v53
	v_add_f32_e32 v48, v48, v54
	v_add_f32_e32 v48, v48, v55
	s_lshl_b32 s30, s22, 12
	s_add_u32 s66, s20, s30
	s_addc_u32 s67, s21, 0
	global_store_dword v1, v40, s[66:67]
	global_store_dword v1, v48, s[66:67] offset:256
	s_add_u32 s22, s22, s12
	s_cmp_ge_u32 s22, 0x8000
	s_cbranch_scc1 .Lgu_done
	s_waitcnt vmcnt(20)
	v_mov_b32_e32 v8, v10
	v_mov_b32_e32 v9, v11
	ds_bpermute_b32 v192, v4, v8
	ds_bpermute_b32 v193, v4, v8 offset:32
	ds_bpermute_b32 v194, v4, v8 offset:64
	ds_bpermute_b32 v195, v4, v8 offset:96
	ds_bpermute_b32 v196, v4, v8 offset:128
	ds_bpermute_b32 v197, v4, v8 offset:160
	ds_bpermute_b32 v198, v4, v8 offset:192
	ds_bpermute_b32 v199, v4, v8 offset:224
	ds_bpermute_b32 v200, v4, v9
	ds_bpermute_b32 v201, v4, v9 offset:32
	ds_bpermute_b32 v202, v4, v9 offset:64
	ds_bpermute_b32 v203, v4, v9 offset:96
	ds_bpermute_b32 v204, v4, v9 offset:128
	ds_bpermute_b32 v205, v4, v9 offset:160
	ds_bpermute_b32 v206, v4, v9 offset:192
	ds_bpermute_b32 v207, v4, v9 offset:224
	s_mov_b32 s31, s12
	s_add_u32 s26, s22, s31
	s_min_u32 s26, s26, 0x7fff
	s_mov_b32 s42, s26
	s_mul_i32 s31, s12, 2
	s_add_u32 s26, s22, s31
	s_min_u32 s26, s26, 0x7fff
	s_lshl_b32 s30, s26, 9
	s_add_u32 s40, s18, s30
	s_addc_u32 s41, s19, 0
	global_load_dword v10, v1, s[40:41]
	global_load_dword v11, v1, s[40:41] offset:256
	s_waitcnt lgkmcnt(0)
	s_lshl_b32 s30, s42, 12
	s_add_u32 s66, s16, s30
	s_addc_u32 s67, s17, 0
	global_load_dwordx4 v[208:211], v7, s[66:67]
	global_load_dwordx4 v[212:215], v7, s[66:67] offset:16
	global_load_dwordx4 v[216:219], v7, s[66:67] offset:32
	global_load_dwordx4 v[220:223], v7, s[66:67] offset:48
	v_lshl_add_u32 v192, v192, 7, v3
	global_load_dwordx4 v[64:67], v192, s[14:15]
	v_lshl_add_u32 v193, v193, 7, v3
	global_load_dwordx4 v[68:71], v193, s[14:15]
	v_lshl_add_u32 v194, v194, 7, v3
	global_load_dwordx4 v[72:75], v194, s[14:15]
	v_lshl_add_u32 v195, v195, 7, v3
	global_load_dwordx4 v[76:79], v195, s[14:15]
	v_lshl_add_u32 v196, v196, 7, v3
	global_load_dwordx4 v[80:83], v196, s[14:15]
	v_lshl_add_u32 v197, v197, 7, v3
	global_load_dwordx4 v[84:87], v197, s[14:15]
	v_lshl_add_u32 v198, v198, 7, v3
	global_load_dwordx4 v[88:91], v198, s[14:15]
	v_lshl_add_u32 v199, v199, 7, v3
	global_load_dwordx4 v[92:95], v199, s[14:15]
	v_lshl_add_u32 v200, v200, 7, v3
	global_load_dwordx4 v[96:99], v200, s[14:15]
	v_lshl_add_u32 v201, v201, 7, v3
	global_load_dwordx4 v[100:103], v201, s[14:15]
	v_lshl_add_u32 v202, v202, 7, v3
	global_load_dwordx4 v[104:107], v202, s[14:15]
	v_lshl_add_u32 v203, v203, 7, v3
	global_load_dwordx4 v[108:111], v203, s[14:15]
	v_lshl_add_u32 v204, v204, 7, v3
	global_load_dwordx4 v[112:115], v204, s[14:15]
	v_lshl_add_u32 v205, v205, 7, v3
	global_load_dwordx4 v[116:119], v205, s[14:15]
	v_lshl_add_u32 v206, v206, 7, v3
	global_load_dwordx4 v[120:123], v206, s[14:15]
	v_lshl_add_u32 v207, v207, 7, v3
	global_load_dwordx4 v[124:127], v207, s[14:15]
	s_waitcnt vmcnt(22)
	v_cvt_pk_f32_fp8_e32 v[40:41], v128
	v_cvt_pk_f32_fp8_sdwa v[42:43], v128 src0_sel:WORD_1
	v_cvt_pk_f32_fp8_e32 v[44:45], v129
	v_cvt_pk_f32_fp8_sdwa v[46:47], v129 src0_sel:WORD_1
	v_cvt_pk_f32_fp8_e32 v[48:49], v130
	v_cvt_pk_f32_fp8_sdwa v[50:51], v130 src0_sel:WORD_1
	v_cvt_pk_f32_fp8_e32 v[52:53], v131
	v_cvt_pk_f32_fp8_sdwa v[54:55], v131 src0_sel:WORD_1
	v_pk_mul_f32 v[24:25], v[40:41], v[224:225]
	v_pk_fma_f32 v[24:25], v[42:43], v[226:227], v[24:25]
	v_pk_fma_f32 v[24:25], v[44:45], v[228:229], v[24:25]
	v_pk_fma_f32 v[24:25], v[46:47], v[230:231], v[24:25]
	v_pk_fma_f32 v[24:25], v[48:49], v[232:233], v[24:25]
	v_pk_fma_f32 v[24:25], v[50:51], v[234:235], v[24:25]
	v_pk_fma_f32 v[24:25], v[52:53], v[236:237], v[24:25]
	v_pk_fma_f32 v[24:25], v[54:55], v[238:239], v[24:25]
	v_add_f32_e32 v56, v24, v25
	ds_write_b32 v5, v56
	v_cvt_pk_f32_fp8_e32 v[40:41], v132
	v_cvt_pk_f32_fp8_sdwa v[42:43], v132 src0_sel:WORD_1
	v_cvt_pk_f32_fp8_e32 v[44:45], v133
	v_cvt_pk_f32_fp8_sdwa v[46:47], v133 src0_sel:WORD_1
	v_cvt_pk_f32_fp8_e32 v[48:49], v134
	v_cvt_pk_f32_fp8_sdwa v[50:51], v134 src0_sel:WORD_1
	v_cvt_pk_f32_fp8_e32 v[52:53], v135
	v_cvt_pk_f32_fp8_sdwa v[54:55], v135 src0_sel:WORD_1
	v_pk_mul_f32 v[24:25], v[40:41], v[224:225]
	v_pk_fma_f32 v[24:25], v[42:43], v[226:227], v[24:25]
	v_pk_fma_f32 v[24:25], v[44:45], v[228:229], v[24:25]
	v_pk_fma_f32 v[24:25], v[46:47], v[230:231], v[24:25]
	v_pk_fma_f32 v[24:25], v[48:49], v[232:233], v[24:25]
	v_pk_fma_f32 v[24:25], v[50:51], v[234:235], v[24:25]
	v_pk_fma_f32 v[24:25], v[52:53], v[236:237], v[24:25]
	v_pk_fma_f32 v[24:25], v[54:55], v[238:239], v[24:25]
	v_add_f32_e32 v56, v24, v25
	ds_write_b32 v5, v56 offset:256
	v_cvt_pk_f32_fp8_e32 v[40:41], v136
	v_cvt_pk_f32_fp8_sdwa v[42:43], v136 src0_sel:WORD_1
	v_cvt_pk_f32_fp8_e32 v[44:45], v137
	v_cvt_pk_f32_fp8_sdwa v[46:47], v137 src0_sel:WORD_1
	v_cvt_pk_f32_fp8_e32 v[48:49], v138
	v_cvt_pk_f32_fp8_sdwa v[50:51], v138 src0_sel:WORD_1
	v_cvt_pk_f32_fp8_e32 v[52:53], v139
	v_cvt_pk_f32_fp8_sdwa v[54:55], v139 src0_sel:WORD_1
	v_pk_mul_f32 v[24:25], v[40:41], v[224:225]
	v_pk_fma_f32 v[24:25], v[42:43], v[226:227], v[24:25]
	v_pk_fma_f32 v[24:25], v[44:45], v[228:229], v[24:25]
	v_pk_fma_f32 v[24:25], v[46:47], v[230:231], v[24:25]
	v_pk_fma_f32 v[24:25], v[48:49], v[232:233], v[24:25]
	v_pk_fma_f32 v[24:25], v[50:51], v[234:235], v[24:25]
	v_pk_fma_f32 v[24:25], v[52:53], v[236:237], v[24:25]
	v_pk_fma_f32 v[24:25], v[54:55], v[238:239], v[24:25]
	v_add_f32_e32 v56, v24, v25
	ds_write_b32 v5, v56 offset:512
	v_cvt_pk_f32_fp8_e32 v[40:41], v140
	v_cvt_pk_f32_fp8_sdwa v[42:43], v140 src0_sel:WORD_1
	v_cvt_pk_f32_fp8_e32 v[44:45], v141
	v_cvt_pk_f32_fp8_sdwa v[46:47], v141 src0_sel:WORD_1
	v_cvt_pk_f32_fp8_e32 v[48:49], v142
	v_cvt_pk_f32_fp8_sdwa v[50:51], v142 src0_sel:WORD_1
	v_cvt_pk_f32_fp8_e32 v[52:53], v143
	v_cvt_pk_f32_fp8_sdwa v[54:55], v143 src0_sel:WORD_1
	v_pk_mul_f32 v[24:25], v[40:41], v[224:225]
	v_pk_fma_f32 v[24:25], v[42:43], v[226:227], v[24:25]
	v_pk_fma_f32 v[24:25], v[44:45], v[228:229], v[24:25]
	v_pk_fma_f32 v[24:25], v[46:47], v[230:231], v[24:25]
	v_pk_fma_f32 v[24:25], v[48:49], v[232:233], v[24:25]
	v_pk_fma_f32 v[24:25], v[50:51], v[234:235], v[24:25]
	v_pk_fma_f32 v[24:25], v[52:53], v[236:237], v[24:25]
	v_pk_fma_f32 v[24:25], v[54:55], v[238:239], v[24:25]
	v_add_f32_e32 v56, v24, v25
	ds_write_b32 v5, v56 offset:768
	v_cvt_pk_f32_fp8_e32 v[40:41], v144
	v_cvt_pk_f32_fp8_sdwa v[42:43], v144 src0_sel:WORD_1
	v_cvt_pk_f32_fp8_e32 v[44:45], v145
	v_cvt_pk_f32_fp8_sdwa v[46:47], v145 src0_sel:WORD_1
	v_cvt_pk_f32_fp8_e32 v[48:49], v146
	v_cvt_pk_f32_fp8_sdwa v[50:51], v146 src0_sel:WORD_1
	v_cvt_pk_f32_fp8_e32 v[52:53], v147
	v_cvt_pk_f32_fp8_sdwa v[54:55], v147 src0_sel:WORD_1
	v_pk_mul_f32 v[24:25], v[40:41], v[224:225]
	v_pk_fma_f32 v[24:25], v[42:43], v[226:227], v[24:25]
	v_pk_fma_f32 v[24:25], v[44:45], v[228:229], v[24:25]
	v_pk_fma_f32 v[24:25], v[46:47], v[230:231], v[24:25]
	v_pk_fma_f32 v[24:25], v[48:49], v[232:233], v[24:25]
	v_pk_fma_f32 v[24:25], v[50:51], v[234:235], v[24:25]
	v_pk_fma_f32 v[24:25], v[52:53], v[236:237], v[24:25]
	v_pk_fma_f32 v[24:25], v[54:55], v[238:239], v[24:25]
	v_add_f32_e32 v56, v24, v25
	ds_write_b32 v5, v56 offset:1024
	v_cvt_pk_f32_fp8_e32 v[40:41], v148
	v_cvt_pk_f32_fp8_sdwa v[42:43], v148 src0_sel:WORD_1
	v_cvt_pk_f32_fp8_e32 v[44:45], v149
	v_cvt_pk_f32_fp8_sdwa v[46:47], v149 src0_sel:WORD_1
	v_cvt_pk_f32_fp8_e32 v[48:49], v150
	v_cvt_pk_f32_fp8_sdwa v[50:51], v150 src0_sel:WORD_1
	v_cvt_pk_f32_fp8_e32 v[52:53], v151
	v_cvt_pk_f32_fp8_sdwa v[54:55], v151 src0_sel:WORD_1
	v_pk_mul_f32 v[24:25], v[40:41], v[224:225]
	v_pk_fma_f32 v[24:25], v[42:43], v[226:227], v[24:25]
	v_pk_fma_f32 v[24:25], v[44:45], v[228:229], v[24:25]
	v_pk_fma_f32 v[24:25], v[46:47], v[230:231], v[24:25]
	v_pk_fma_f32 v[24:25], v[48:49], v[232:233], v[24:25]
	v_pk_fma_f32 v[24:25], v[50:51], v[234:235], v[24:25]
	v_pk_fma_f32 v[24:25], v[52:53], v[236:237], v[24:25]
	v_pk_fma_f32 v[24:25], v[54:55], v[238:239], v[24:25]
	v_add_f32_e32 v56, v24, v25
	ds_write_b32 v5, v56 offset:1280
	v_cvt_pk_f32_fp8_e32 v[40:41], v152
	v_cvt_pk_f32_fp8_sdwa v[42:43], v152 src0_sel:WORD_1
	v_cvt_pk_f32_fp8_e32 v[44:45], v153
	v_cvt_pk_f32_fp8_sdwa v[46:47], v153 src0_sel:WORD_1
	v_cvt_pk_f32_fp8_e32 v[48:49], v154
	v_cvt_pk_f32_fp8_sdwa v[50:51], v154 src0_sel:WORD_1
	v_cvt_pk_f32_fp8_e32 v[52:53], v155
	v_cvt_pk_f32_fp8_sdwa v[54:55], v155 src0_sel:WORD_1
	v_pk_mul_f32 v[24:25], v[40:41], v[224:225]
	v_pk_fma_f32 v[24:25], v[42:43], v[226:227], v[24:25]
	v_pk_fma_f32 v[24:25], v[44:45], v[228:229], v[24:25]
	v_pk_fma_f32 v[24:25], v[46:47], v[230:231], v[24:25]
	v_pk_fma_f32 v[24:25], v[48:49], v[232:233], v[24:25]
	v_pk_fma_f32 v[24:25], v[50:51], v[234:235], v[24:25]
	v_pk_fma_f32 v[24:25], v[52:53], v[236:237], v[24:25]
	v_pk_fma_f32 v[24:25], v[54:55], v[238:239], v[24:25]
	v_add_f32_e32 v56, v24, v25
	ds_write_b32 v5, v56 offset:1536
	v_cvt_pk_f32_fp8_e32 v[40:41], v156
	v_cvt_pk_f32_fp8_sdwa v[42:43], v156 src0_sel:WORD_1
	v_cvt_pk_f32_fp8_e32 v[44:45], v157
	v_cvt_pk_f32_fp8_sdwa v[46:47], v157 src0_sel:WORD_1
	v_cvt_pk_f32_fp8_e32 v[48:49], v158
	v_cvt_pk_f32_fp8_sdwa v[50:51], v158 src0_sel:WORD_1
	v_cvt_pk_f32_fp8_e32 v[52:53], v159
	v_cvt_pk_f32_fp8_sdwa v[54:55], v159 src0_sel:WORD_1
	v_pk_mul_f32 v[24:25], v[40:41], v[224:225]
	v_pk_fma_f32 v[24:25], v[42:43], v[226:227], v[24:25]
	v_pk_fma_f32 v[24:25], v[44:45], v[228:229], v[24:25]
	v_pk_fma_f32 v[24:25], v[46:47], v[230:231], v[24:25]
	v_pk_fma_f32 v[24:25], v[48:49], v[232:233], v[24:25]
	v_pk_fma_f32 v[24:25], v[50:51], v[234:235], v[24:25]
	v_pk_fma_f32 v[24:25], v[52:53], v[236:237], v[24:25]
	v_pk_fma_f32 v[24:25], v[54:55], v[238:239], v[24:25]
	v_add_f32_e32 v56, v24, v25
	ds_write_b32 v5, v56 offset:1792
	v_cvt_pk_f32_fp8_e32 v[40:41], v160
	v_cvt_pk_f32_fp8_sdwa v[42:43], v160 src0_sel:WORD_1
	v_cvt_pk_f32_fp8_e32 v[44:45], v161
	v_cvt_pk_f32_fp8_sdwa v[46:47], v161 src0_sel:WORD_1
	v_cvt_pk_f32_fp8_e32 v[48:49], v162
	v_cvt_pk_f32_fp8_sdwa v[50:51], v162 src0_sel:WORD_1
	v_cvt_pk_f32_fp8_e32 v[52:53], v163
	v_cvt_pk_f32_fp8_sdwa v[54:55], v163 src0_sel:WORD_1
	v_pk_mul_f32 v[24:25], v[40:41], v[224:225]
	v_pk_fma_f32 v[24:25], v[42:43], v[226:227], v[24:25]
	v_pk_fma_f32 v[24:25], v[44:45], v[228:229], v[24:25]
	v_pk_fma_f32 v[24:25], v[46:47], v[230:231], v[24:25]
	v_pk_fma_f32 v[24:25], v[48:49], v[232:233], v[24:25]
	v_pk_fma_f32 v[24:25], v[50:51], v[234:235], v[24:25]
	v_pk_fma_f32 v[24:25], v[52:53], v[236:237], v[24:25]
	v_pk_fma_f32 v[24:25], v[54:55], v[238:239], v[24:25]
	v_add_f32_e32 v56, v24, v25
	ds_write_b32 v5, v56 offset:2048
	v_cvt_pk_f32_fp8_e32 v[40:41], v164
	v_cvt_pk_f32_fp8_sdwa v[42:43], v164 src0_sel:WORD_1
	v_cvt_pk_f32_fp8_e32 v[44:45], v165
	v_cvt_pk_f32_fp8_sdwa v[46:47], v165 src0_sel:WORD_1
	v_cvt_pk_f32_fp8_e32 v[48:49], v166
	v_cvt_pk_f32_fp8_sdwa v[50:51], v166 src0_sel:WORD_1
	v_cvt_pk_f32_fp8_e32 v[52:53], v167
	v_cvt_pk_f32_fp8_sdwa v[54:55], v167 src0_sel:WORD_1
	v_pk_mul_f32 v[24:25], v[40:41], v[224:225]
	v_pk_fma_f32 v[24:25], v[42:43], v[226:227], v[24:25]
	v_pk_fma_f32 v[24:25], v[44:45], v[228:229], v[24:25]
	v_pk_fma_f32 v[24:25], v[46:47], v[230:231], v[24:25]
	v_pk_fma_f32 v[24:25], v[48:49], v[232:233], v[24:25]
	v_pk_fma_f32 v[24:25], v[50:51], v[234:235], v[24:25]
	v_pk_fma_f32 v[24:25], v[52:53], v[236:237], v[24:25]
	v_pk_fma_f32 v[24:25], v[54:55], v[238:239], v[24:25]
	v_add_f32_e32 v56, v24, v25
	ds_write_b32 v5, v56 offset:2304
	v_cvt_pk_f32_fp8_e32 v[40:41], v168
	v_cvt_pk_f32_fp8_sdwa v[42:43], v168 src0_sel:WORD_1
	v_cvt_pk_f32_fp8_e32 v[44:45], v169
	v_cvt_pk_f32_fp8_sdwa v[46:47], v169 src0_sel:WORD_1
	v_cvt_pk_f32_fp8_e32 v[48:49], v170
	v_cvt_pk_f32_fp8_sdwa v[50:51], v170 src0_sel:WORD_1
	v_cvt_pk_f32_fp8_e32 v[52:53], v171
	v_cvt_pk_f32_fp8_sdwa v[54:55], v171 src0_sel:WORD_1
	v_pk_mul_f32 v[24:25], v[40:41], v[224:225]
	v_pk_fma_f32 v[24:25], v[42:43], v[226:227], v[24:25]
	v_pk_fma_f32 v[24:25], v[44:45], v[228:229], v[24:25]
	v_pk_fma_f32 v[24:25], v[46:47], v[230:231], v[24:25]
	v_pk_fma_f32 v[24:25], v[48:49], v[232:233], v[24:25]
	v_pk_fma_f32 v[24:25], v[50:51], v[234:235], v[24:25]
	v_pk_fma_f32 v[24:25], v[52:53], v[236:237], v[24:25]
	v_pk_fma_f32 v[24:25], v[54:55], v[238:239], v[24:25]
	v_add_f32_e32 v56, v24, v25
	ds_write_b32 v5, v56 offset:2560
	v_cvt_pk_f32_fp8_e32 v[40:41], v172
	v_cvt_pk_f32_fp8_sdwa v[42:43], v172 src0_sel:WORD_1
	v_cvt_pk_f32_fp8_e32 v[44:45], v173
	v_cvt_pk_f32_fp8_sdwa v[46:47], v173 src0_sel:WORD_1
	v_cvt_pk_f32_fp8_e32 v[48:49], v174
	v_cvt_pk_f32_fp8_sdwa v[50:51], v174 src0_sel:WORD_1
	v_cvt_pk_f32_fp8_e32 v[52:53], v175
	v_cvt_pk_f32_fp8_sdwa v[54:55], v175 src0_sel:WORD_1
	v_pk_mul_f32 v[24:25], v[40:41], v[224:225]
	v_pk_fma_f32 v[24:25], v[42:43], v[226:227], v[24:25]
	v_pk_fma_f32 v[24:25], v[44:45], v[228:229], v[24:25]
	v_pk_fma_f32 v[24:25], v[46:47], v[230:231], v[24:25]
	v_pk_fma_f32 v[24:25], v[48:49], v[232:233], v[24:25]
	v_pk_fma_f32 v[24:25], v[50:51], v[234:235], v[24:25]
	v_pk_fma_f32 v[24:25], v[52:53], v[236:237], v[24:25]
	v_pk_fma_f32 v[24:25], v[54:55], v[238:239], v[24:25]
	v_add_f32_e32 v56, v24, v25
	ds_write_b32 v5, v56 offset:2816
	v_cvt_pk_f32_fp8_e32 v[40:41], v176
	v_cvt_pk_f32_fp8_sdwa v[42:43], v176 src0_sel:WORD_1
	v_cvt_pk_f32_fp8_e32 v[44:45], v177
	v_cvt_pk_f32_fp8_sdwa v[46:47], v177 src0_sel:WORD_1
	v_cvt_pk_f32_fp8_e32 v[48:49], v178
	v_cvt_pk_f32_fp8_sdwa v[50:51], v178 src0_sel:WORD_1
	v_cvt_pk_f32_fp8_e32 v[52:53], v179
	v_cvt_pk_f32_fp8_sdwa v[54:55], v179 src0_sel:WORD_1
	v_pk_mul_f32 v[24:25], v[40:41], v[224:225]
	v_pk_fma_f32 v[24:25], v[42:43], v[226:227], v[24:25]
	v_pk_fma_f32 v[24:25], v[44:45], v[228:229], v[24:25]
	v_pk_fma_f32 v[24:25], v[46:47], v[230:231], v[24:25]
	v_pk_fma_f32 v[24:25], v[48:49], v[232:233], v[24:25]
	v_pk_fma_f32 v[24:25], v[50:51], v[234:235], v[24:25]
	v_pk_fma_f32 v[24:25], v[52:53], v[236:237], v[24:25]
	v_pk_fma_f32 v[24:25], v[54:55], v[238:239], v[24:25]
	v_add_f32_e32 v56, v24, v25
	ds_write_b32 v5, v56 offset:3072
	v_cvt_pk_f32_fp8_e32 v[40:41], v180
	v_cvt_pk_f32_fp8_sdwa v[42:43], v180 src0_sel:WORD_1
	v_cvt_pk_f32_fp8_e32 v[44:45], v181
	v_cvt_pk_f32_fp8_sdwa v[46:47], v181 src0_sel:WORD_1
	v_cvt_pk_f32_fp8_e32 v[48:49], v182
	v_cvt_pk_f32_fp8_sdwa v[50:51], v182 src0_sel:WORD_1
	v_cvt_pk_f32_fp8_e32 v[52:53], v183
	v_cvt_pk_f32_fp8_sdwa v[54:55], v183 src0_sel:WORD_1
	v_pk_mul_f32 v[24:25], v[40:41], v[224:225]
	v_pk_fma_f32 v[24:25], v[42:43], v[226:227], v[24:25]
	v_pk_fma_f32 v[24:25], v[44:45], v[228:229], v[24:25]
	v_pk_fma_f32 v[24:25], v[46:47], v[230:231], v[24:25]
	v_pk_fma_f32 v[24:25], v[48:49], v[232:233], v[24:25]
	v_pk_fma_f32 v[24:25], v[50:51], v[234:235], v[24:25]
	v_pk_fma_f32 v[24:25], v[52:53], v[236:237], v[24:25]
	v_pk_fma_f32 v[24:25], v[54:55], v[238:239], v[24:25]
	v_add_f32_e32 v56, v24, v25
	ds_write_b32 v5, v56 offset:3328
	v_cvt_pk_f32_fp8_e32 v[40:41], v184
	v_cvt_pk_f32_fp8_sdwa v[42:43], v184 src0_sel:WORD_1
	v_cvt_pk_f32_fp8_e32 v[44:45], v185
	v_cvt_pk_f32_fp8_sdwa v[46:47], v185 src0_sel:WORD_1
	v_cvt_pk_f32_fp8_e32 v[48:49], v186
	v_cvt_pk_f32_fp8_sdwa v[50:51], v186 src0_sel:WORD_1
	v_cvt_pk_f32_fp8_e32 v[52:53], v187
	v_cvt_pk_f32_fp8_sdwa v[54:55], v187 src0_sel:WORD_1
	v_pk_mul_f32 v[24:25], v[40:41], v[224:225]
	v_pk_fma_f32 v[24:25], v[42:43], v[226:227], v[24:25]
	v_pk_fma_f32 v[24:25], v[44:45], v[228:229], v[24:25]
	v_pk_fma_f32 v[24:25], v[46:47], v[230:231], v[24:25]
	v_pk_fma_f32 v[24:25], v[48:49], v[232:233], v[24:25]
	v_pk_fma_f32 v[24:25], v[50:51], v[234:235], v[24:25]
	v_pk_fma_f32 v[24:25], v[52:53], v[236:237], v[24:25]
	v_pk_fma_f32 v[24:25], v[54:55], v[238:239], v[24:25]
	v_add_f32_e32 v56, v24, v25
	ds_write_b32 v5, v56 offset:3584
	v_cvt_pk_f32_fp8_e32 v[40:41], v188
	v_cvt_pk_f32_fp8_sdwa v[42:43], v188 src0_sel:WORD_1
	v_cvt_pk_f32_fp8_e32 v[44:45], v189
	v_cvt_pk_f32_fp8_sdwa v[46:47], v189 src0_sel:WORD_1
	v_cvt_pk_f32_fp8_e32 v[48:49], v190
	v_cvt_pk_f32_fp8_sdwa v[50:51], v190 src0_sel:WORD_1
	v_cvt_pk_f32_fp8_e32 v[52:53], v191
	v_cvt_pk_f32_fp8_sdwa v[54:55], v191 src0_sel:WORD_1
	v_pk_mul_f32 v[24:25], v[40:41], v[224:225]
	v_pk_fma_f32 v[24:25], v[42:43], v[226:227], v[24:25]
	v_pk_fma_f32 v[24:25], v[44:45], v[228:229], v[24:25]
	v_pk_fma_f32 v[24:25], v[46:47], v[230:231], v[24:25]
	v_pk_fma_f32 v[24:25], v[48:49], v[232:233], v[24:25]
	v_pk_fma_f32 v[24:25], v[50:51], v[234:235], v[24:25]
	v_pk_fma_f32 v[24:25], v[52:53], v[236:237], v[24:25]
	v_pk_fma_f32 v[24:25], v[54:55], v[238:239], v[24:25]
	v_add_f32_e32 v56, v24, v25
	ds_write_b32 v5, v56 offset:3840
	ds_read_b128 v[40:43], v6
	ds_read_b128 v[44:47], v6 offset:16
	ds_read_b128 v[48:51], v6 offset:2048
	ds_read_b128 v[52:55], v6 offset:2064
	s_waitcnt lgkmcnt(2)
	v_add_f32_e32 v40, v40, v41
	v_add_f32_e32 v40, v40, v42
	v_add_f32_e32 v40, v40, v43
	v_add_f32_e32 v40, v40, v44
	v_add_f32_e32 v40, v40, v45
	v_add_f32_e32 v40, v40, v46
	v_add_f32_e32 v40, v40, v47
	s_waitcnt lgkmcnt(0)
	v_add_f32_e32 v48, v48, v49
	v_add_f32_e32 v48, v48, v50
	v_add_f32_e32 v48, v48, v51
	v_add_f32_e32 v48, v48, v52
	v_add_f32_e32 v48, v48, v53
	v_add_f32_e32 v48, v48, v54
	v_add_f32_e32 v48, v48, v55
	s_lshl_b32 s30, s22, 12
	s_add_u32 s66, s20, s30
	s_addc_u32 s67, s21, 0
	global_store_dword v1, v40, s[66:67]
	global_store_dword v1, v48, s[66:67] offset:256
	s_add_u32 s22, s22, s12
	s_cmp_ge_u32 s22, 0x8000
	s_cbranch_scc0 .Lgu_loop

.Lgv_loop:
	s_waitcnt vmcnt(16)
	v_mov_b32_e32 v8, v10
	v_mov_b32_e32 v9, v11
	v_mov_b32_e32 v14, v16
	v_mov_b32_e32 v15, v17
	v_mov_b32_e32 v20, v22
	v_mov_b32_e32 v21, v23
	ds_bpermute_b32 v192, v4, v8
	ds_bpermute_b32 v193, v4, v8 offset:32
	ds_bpermute_b32 v194, v4, v8 offset:64
	ds_bpermute_b32 v195, v4, v8 offset:96
	ds_bpermute_b32 v196, v4, v8 offset:128
	ds_bpermute_b32 v197, v4, v8 offset:160
	ds_bpermute_b32 v198, v4, v8 offset:192
	ds_bpermute_b32 v199, v4, v8 offset:224
	ds_bpermute_b32 v200, v4, v9
	ds_bpermute_b32 v201, v4, v9 offset:32
	ds_bpermute_b32 v202, v4, v9 offset:64
	ds_bpermute_b32 v203, v4, v9 offset:96
	ds_bpermute_b32 v204, v4, v9 offset:128
	ds_bpermute_b32 v205, v4, v9 offset:160
	ds_bpermute_b32 v206, v4, v9 offset:192
	ds_bpermute_b32 v207, v4, v9 offset:224
	s_mov_b32 s31, s12
	s_add_u32 s26, s22, s31
	s_min_u32 s26, s26, 0x7fff
	s_mov_b32 s42, s26
	s_mul_i32 s31, s12, 2
	s_add_u32 s26, s22, s31
	s_min_u32 s26, s26, 0x7fff
	s_lshl_b32 s30, s26, 9
	s_add_u32 s40, s18, s30
	s_addc_u32 s41, s19, 0
	global_load_dword v10, v1, s[40:41]
	global_load_dword v11, v1, s[40:41] offset:256
	s_add_u32 s64, s20, s30
	s_addc_u32 s65, s21, 0
	global_load_dword v16, v1, s[64:65]
	global_load_dword v17, v1, s[64:65] offset:256
	s_lshl_b32 s30, s26, 12
	s_add_u32 s66, s16, s30
	s_addc_u32 s67, s17, 0
	global_load_dwordx2 v[22:23], v2, s[66:67]
	ds_bpermute_b32 v208, v4, v12
	ds_bpermute_b32 v210, v4, v12 offset:32
	ds_bpermute_b32 v212, v4, v12 offset:64
	ds_bpermute_b32 v214, v4, v12 offset:96
	ds_bpermute_b32 v216, v4, v12 offset:128
	ds_bpermute_b32 v218, v4, v12 offset:160
	ds_bpermute_b32 v220, v4, v12 offset:192
	ds_bpermute_b32 v222, v4, v12 offset:224
	ds_bpermute_b32 v224, v4, v13
	ds_bpermute_b32 v226, v4, v13 offset:32
	ds_bpermute_b32 v228, v4, v13 offset:64
	ds_bpermute_b32 v230, v4, v13 offset:96
	ds_bpermute_b32 v232, v4, v13 offset:128
	ds_bpermute_b32 v234, v4, v13 offset:160
	ds_bpermute_b32 v236, v4, v13 offset:192
	ds_bpermute_b32 v238, v4, v13 offset:224
	s_waitcnt lgkmcnt(0)
	v_lshl_add_u32 v192, v192, 7, v3
	global_load_dwordx4 v[128:131], v192, s[14:15]
	v_lshl_add_u32 v193, v193, 7, v3
	global_load_dwordx4 v[132:135], v193, s[14:15]
	v_lshl_add_u32 v194, v194, 7, v3
	global_load_dwordx4 v[136:139], v194, s[14:15]
	v_lshl_add_u32 v195, v195, 7, v3
	global_load_dwordx4 v[140:143], v195, s[14:15]
	v_lshl_add_u32 v196, v196, 7, v3
	global_load_dwordx4 v[144:147], v196, s[14:15]
	v_lshl_add_u32 v197, v197, 7, v3
	global_load_dwordx4 v[148:151], v197, s[14:15]
	v_lshl_add_u32 v198, v198, 7, v3
	global_load_dwordx4 v[152:155], v198, s[14:15]
	v_lshl_add_u32 v199, v199, 7, v3
	global_load_dwordx4 v[156:159], v199, s[14:15]
	v_lshl_add_u32 v200, v200, 7, v3
	global_load_dwordx4 v[160:163], v200, s[14:15]
	v_lshl_add_u32 v201, v201, 7, v3
	global_load_dwordx4 v[164:167], v201, s[14:15]
	v_lshl_add_u32 v202, v202, 7, v3
	global_load_dwordx4 v[168:171], v202, s[14:15]
	v_lshl_add_u32 v203, v203, 7, v3
	global_load_dwordx4 v[172:175], v203, s[14:15]
	v_lshl_add_u32 v204, v204, 7, v3
	global_load_dwordx4 v[176:179], v204, s[14:15]
	v_lshl_add_u32 v205, v205, 7, v3
	global_load_dwordx4 v[180:183], v205, s[14:15]
	v_lshl_add_u32 v206, v206, 7, v3
	global_load_dwordx4 v[184:187], v206, s[14:15]
	v_lshl_add_u32 v207, v207, 7, v3
	global_load_dwordx4 v[188:191], v207, s[14:15]
	s_waitcnt vmcnt(21)
	v_cvt_pk_f32_fp8_e32 v[40:41], v64
	v_cvt_pk_f32_fp8_sdwa v[42:43], v64 src0_sel:WORD_1
	v_cvt_pk_f32_fp8_e32 v[44:45], v65
	v_cvt_pk_f32_fp8_sdwa v[46:47], v65 src0_sel:WORD_1
	v_cvt_pk_f32_fp8_e32 v[48:49], v66
	v_cvt_pk_f32_fp8_sdwa v[50:51], v66 src0_sel:WORD_1
	v_cvt_pk_f32_fp8_e32 v[52:53], v67
	v_cvt_pk_f32_fp8_sdwa v[54:55], v67 src0_sel:WORD_1
	v_pk_mul_f32 v[24:25], v[40:41], v[208:209] op_sel_hi:[1,0]
	v_pk_mul_f32 v[26:27], v[42:43], v[208:209] op_sel_hi:[1,0]
	v_pk_mul_f32 v[28:29], v[44:45], v[208:209] op_sel_hi:[1,0]
	v_pk_mul_f32 v[30:31], v[46:47], v[208:209] op_sel_hi:[1,0]
	v_pk_mul_f32 v[32:33], v[48:49], v[208:209] op_sel_hi:[1,0]
	v_pk_mul_f32 v[34:35], v[50:51], v[208:209] op_sel_hi:[1,0]
	v_pk_mul_f32 v[36:37], v[52:53], v[208:209] op_sel_hi:[1,0]
	v_pk_mul_f32 v[38:39], v[54:55], v[208:209] op_sel_hi:[1,0]
	v_cvt_pk_f32_fp8_e32 v[40:41], v68
	v_cvt_pk_f32_fp8_sdwa v[42:43], v68 src0_sel:WORD_1
	v_cvt_pk_f32_fp8_e32 v[44:45], v69
	v_cvt_pk_f32_fp8_sdwa v[46:47], v69 src0_sel:WORD_1
	v_cvt_pk_f32_fp8_e32 v[48:49], v70
	v_cvt_pk_f32_fp8_sdwa v[50:51], v70 src0_sel:WORD_1
	v_cvt_pk_f32_fp8_e32 v[52:53], v71
	v_cvt_pk_f32_fp8_sdwa v[54:55], v71 src0_sel:WORD_1
	v_pk_fma_f32 v[24:25], v[40:41], v[210:211], v[24:25] op_sel_hi:[1,0,1]
	v_pk_fma_f32 v[26:27], v[42:43], v[210:211], v[26:27] op_sel_hi:[1,0,1]
	v_pk_fma_f32 v[28:29], v[44:45], v[210:211], v[28:29] op_sel_hi:[1,0,1]
	v_pk_fma_f32 v[30:31], v[46:47], v[210:211], v[30:31] op_sel_hi:[1,0,1]
	v_pk_fma_f32 v[32:33], v[48:49], v[210:211], v[32:33] op_sel_hi:[1,0,1]
	v_pk_fma_f32 v[34:35], v[50:51], v[210:211], v[34:35] op_sel_hi:[1,0,1]
	v_pk_fma_f32 v[36:37], v[52:53], v[210:211], v[36:37] op_sel_hi:[1,0,1]
	v_pk_fma_f32 v[38:39], v[54:55], v[210:211], v[38:39] op_sel_hi:[1,0,1]
	v_cvt_pk_f32_fp8_e32 v[40:41], v72
	v_cvt_pk_f32_fp8_sdwa v[42:43], v72 src0_sel:WORD_1
	v_cvt_pk_f32_fp8_e32 v[44:45], v73
	v_cvt_pk_f32_fp8_sdwa v[46:47], v73 src0_sel:WORD_1
	v_cvt_pk_f32_fp8_e32 v[48:49], v74
	v_cvt_pk_f32_fp8_sdwa v[50:51], v74 src0_sel:WORD_1
	v_cvt_pk_f32_fp8_e32 v[52:53], v75
	v_cvt_pk_f32_fp8_sdwa v[54:55], v75 src0_sel:WORD_1
	v_pk_fma_f32 v[24:25], v[40:41], v[212:213], v[24:25] op_sel_hi:[1,0,1]
	v_pk_fma_f32 v[26:27], v[42:43], v[212:213], v[26:27] op_sel_hi:[1,0,1]
	v_pk_fma_f32 v[28:29], v[44:45], v[212:213], v[28:29] op_sel_hi:[1,0,1]
	v_pk_fma_f32 v[30:31], v[46:47], v[212:213], v[30:31] op_sel_hi:[1,0,1]
	v_pk_fma_f32 v[32:33], v[48:49], v[212:213], v[32:33] op_sel_hi:[1,0,1]
	v_pk_fma_f32 v[34:35], v[50:51], v[212:213], v[34:35] op_sel_hi:[1,0,1]
	v_pk_fma_f32 v[36:37], v[52:53], v[212:213], v[36:37] op_sel_hi:[1,0,1]
	v_pk_fma_f32 v[38:39], v[54:55], v[212:213], v[38:39] op_sel_hi:[1,0,1]
	v_cvt_pk_f32_fp8_e32 v[40:41], v76
	v_cvt_pk_f32_fp8_sdwa v[42:43], v76 src0_sel:WORD_1
	v_cvt_pk_f32_fp8_e32 v[44:45], v77
	v_cvt_pk_f32_fp8_sdwa v[46:47], v77 src0_sel:WORD_1
	v_cvt_pk_f32_fp8_e32 v[48:49], v78
	v_cvt_pk_f32_fp8_sdwa v[50:51], v78 src0_sel:WORD_1
	v_cvt_pk_f32_fp8_e32 v[52:53], v79
	v_cvt_pk_f32_fp8_sdwa v[54:55], v79 src0_sel:WORD_1
	v_pk_fma_f32 v[24:25], v[40:41], v[214:215], v[24:25] op_sel_hi:[1,0,1]
	v_pk_fma_f32 v[26:27], v[42:43], v[214:215], v[26:27] op_sel_hi:[1,0,1]
	v_pk_fma_f32 v[28:29], v[44:45], v[214:215], v[28:29] op_sel_hi:[1,0,1]
	v_pk_fma_f32 v[30:31], v[46:47], v[214:215], v[30:31] op_sel_hi:[1,0,1]
	v_pk_fma_f32 v[32:33], v[48:49], v[214:215], v[32:33] op_sel_hi:[1,0,1]
	v_pk_fma_f32 v[34:35], v[50:51], v[214:215], v[34:35] op_sel_hi:[1,0,1]
	v_pk_fma_f32 v[36:37], v[52:53], v[214:215], v[36:37] op_sel_hi:[1,0,1]
	v_pk_fma_f32 v[38:39], v[54:55], v[214:215], v[38:39] op_sel_hi:[1,0,1]
	v_cvt_pk_f32_fp8_e32 v[40:41], v80
	v_cvt_pk_f32_fp8_sdwa v[42:43], v80 src0_sel:WORD_1
	v_cvt_pk_f32_fp8_e32 v[44:45], v81
	v_cvt_pk_f32_fp8_sdwa v[46:47], v81 src0_sel:WORD_1
	v_cvt_pk_f32_fp8_e32 v[48:49], v82
	v_cvt_pk_f32_fp8_sdwa v[50:51], v82 src0_sel:WORD_1
	v_cvt_pk_f32_fp8_e32 v[52:53], v83
	v_cvt_pk_f32_fp8_sdwa v[54:55], v83 src0_sel:WORD_1
	v_pk_fma_f32 v[24:25], v[40:41], v[216:217], v[24:25] op_sel_hi:[1,0,1]
	v_pk_fma_f32 v[26:27], v[42:43], v[216:217], v[26:27] op_sel_hi:[1,0,1]
	v_pk_fma_f32 v[28:29], v[44:45], v[216:217], v[28:29] op_sel_hi:[1,0,1]
	v_pk_fma_f32 v[30:31], v[46:47], v[216:217], v[30:31] op_sel_hi:[1,0,1]
	v_pk_fma_f32 v[32:33], v[48:49], v[216:217], v[32:33] op_sel_hi:[1,0,1]
	v_pk_fma_f32 v[34:35], v[50:51], v[216:217], v[34:35] op_sel_hi:[1,0,1]
	v_pk_fma_f32 v[36:37], v[52:53], v[216:217], v[36:37] op_sel_hi:[1,0,1]
	v_pk_fma_f32 v[38:39], v[54:55], v[216:217], v[38:39] op_sel_hi:[1,0,1]
	v_cvt_pk_f32_fp8_e32 v[40:41], v84
	v_cvt_pk_f32_fp8_sdwa v[42:43], v84 src0_sel:WORD_1
	v_cvt_pk_f32_fp8_e32 v[44:45], v85
	v_cvt_pk_f32_fp8_sdwa v[46:47], v85 src0_sel:WORD_1
	v_cvt_pk_f32_fp8_e32 v[48:49], v86
	v_cvt_pk_f32_fp8_sdwa v[50:51], v86 src0_sel:WORD_1
	v_cvt_pk_f32_fp8_e32 v[52:53], v87
	v_cvt_pk_f32_fp8_sdwa v[54:55], v87 src0_sel:WORD_1
	v_pk_fma_f32 v[24:25], v[40:41], v[218:219], v[24:25] op_sel_hi:[1,0,1]
	v_pk_fma_f32 v[26:27], v[42:43], v[218:219], v[26:27] op_sel_hi:[1,0,1]
	v_pk_fma_f32 v[28:29], v[44:45], v[218:219], v[28:29] op_sel_hi:[1,0,1]
	v_pk_fma_f32 v[30:31], v[46:47], v[218:219], v[30:31] op_sel_hi:[1,0,1]
	v_pk_fma_f32 v[32:33], v[48:49], v[218:219], v[32:33] op_sel_hi:[1,0,1]
	v_pk_fma_f32 v[34:35], v[50:51], v[218:219], v[34:35] op_sel_hi:[1,0,1]
	v_pk_fma_f32 v[36:37], v[52:53], v[218:219], v[36:37] op_sel_hi:[1,0,1]
	v_pk_fma_f32 v[38:39], v[54:55], v[218:219], v[38:39] op_sel_hi:[1,0,1]
	v_cvt_pk_f32_fp8_e32 v[40:41], v88
	v_cvt_pk_f32_fp8_sdwa v[42:43], v88 src0_sel:WORD_1
	v_cvt_pk_f32_fp8_e32 v[44:45], v89
	v_cvt_pk_f32_fp8_sdwa v[46:47], v89 src0_sel:WORD_1
	v_cvt_pk_f32_fp8_e32 v[48:49], v90
	v_cvt_pk_f32_fp8_sdwa v[50:51], v90 src0_sel:WORD_1
	v_cvt_pk_f32_fp8_e32 v[52:53], v91
	v_cvt_pk_f32_fp8_sdwa v[54:55], v91 src0_sel:WORD_1
	v_pk_fma_f32 v[24:25], v[40:41], v[220:221], v[24:25] op_sel_hi:[1,0,1]
	v_pk_fma_f32 v[26:27], v[42:43], v[220:221], v[26:27] op_sel_hi:[1,0,1]
	v_pk_fma_f32 v[28:29], v[44:45], v[220:221], v[28:29] op_sel_hi:[1,0,1]
	v_pk_fma_f32 v[30:31], v[46:47], v[220:221], v[30:31] op_sel_hi:[1,0,1]
	v_pk_fma_f32 v[32:33], v[48:49], v[220:221], v[32:33] op_sel_hi:[1,0,1]
	v_pk_fma_f32 v[34:35], v[50:51], v[220:221], v[34:35] op_sel_hi:[1,0,1]
	v_pk_fma_f32 v[36:37], v[52:53], v[220:221], v[36:37] op_sel_hi:[1,0,1]
	v_pk_fma_f32 v[38:39], v[54:55], v[220:221], v[38:39] op_sel_hi:[1,0,1]
	v_cvt_pk_f32_fp8_e32 v[40:41], v92
	v_cvt_pk_f32_fp8_sdwa v[42:43], v92 src0_sel:WORD_1
	v_cvt_pk_f32_fp8_e32 v[44:45], v93
	v_cvt_pk_f32_fp8_sdwa v[46:47], v93 src0_sel:WORD_1
	v_cvt_pk_f32_fp8_e32 v[48:49], v94
	v_cvt_pk_f32_fp8_sdwa v[50:51], v94 src0_sel:WORD_1
	v_cvt_pk_f32_fp8_e32 v[52:53], v95
	v_cvt_pk_f32_fp8_sdwa v[54:55], v95 src0_sel:WORD_1
	v_pk_fma_f32 v[24:25], v[40:41], v[222:223], v[24:25] op_sel_hi:[1,0,1]
	v_pk_fma_f32 v[26:27], v[42:43], v[222:223], v[26:27] op_sel_hi:[1,0,1]
	v_pk_fma_f32 v[28:29], v[44:45], v[222:223], v[28:29] op_sel_hi:[1,0,1]
	v_pk_fma_f32 v[30:31], v[46:47], v[222:223], v[30:31] op_sel_hi:[1,0,1]
	v_pk_fma_f32 v[32:33], v[48:49], v[222:223], v[32:33] op_sel_hi:[1,0,1]
	v_pk_fma_f32 v[34:35], v[50:51], v[222:223], v[34:35] op_sel_hi:[1,0,1]
	v_pk_fma_f32 v[36:37], v[52:53], v[222:223], v[36:37] op_sel_hi:[1,0,1]
	v_pk_fma_f32 v[38:39], v[54:55], v[222:223], v[38:39] op_sel_hi:[1,0,1]
	v_cvt_pk_f32_fp8_e32 v[40:41], v96
	v_cvt_pk_f32_fp8_sdwa v[42:43], v96 src0_sel:WORD_1
	v_cvt_pk_f32_fp8_e32 v[44:45], v97
	v_cvt_pk_f32_fp8_sdwa v[46:47], v97 src0_sel:WORD_1
	v_cvt_pk_f32_fp8_e32 v[48:49], v98
	v_cvt_pk_f32_fp8_sdwa v[50:51], v98 src0_sel:WORD_1
	v_cvt_pk_f32_fp8_e32 v[52:53], v99
	v_cvt_pk_f32_fp8_sdwa v[54:55], v99 src0_sel:WORD_1
	v_pk_fma_f32 v[24:25], v[40:41], v[224:225], v[24:25] op_sel_hi:[1,0,1]
	v_pk_fma_f32 v[26:27], v[42:43], v[224:225], v[26:27] op_sel_hi:[1,0,1]
	v_pk_fma_f32 v[28:29], v[44:45], v[224:225], v[28:29] op_sel_hi:[1,0,1]
	v_pk_fma_f32 v[30:31], v[46:47], v[224:225], v[30:31] op_sel_hi:[1,0,1]
	v_pk_fma_f32 v[32:33], v[48:49], v[224:225], v[32:33] op_sel_hi:[1,0,1]
	v_pk_fma_f32 v[34:35], v[50:51], v[224:225], v[34:35] op_sel_hi:[1,0,1]
	v_pk_fma_f32 v[36:37], v[52:53], v[224:225], v[36:37] op_sel_hi:[1,0,1]
	v_pk_fma_f32 v[38:39], v[54:55], v[224:225], v[38:39] op_sel_hi:[1,0,1]
	v_cvt_pk_f32_fp8_e32 v[40:41], v100
	v_cvt_pk_f32_fp8_sdwa v[42:43], v100 src0_sel:WORD_1
	v_cvt_pk_f32_fp8_e32 v[44:45], v101
	v_cvt_pk_f32_fp8_sdwa v[46:47], v101 src0_sel:WORD_1
	v_cvt_pk_f32_fp8_e32 v[48:49], v102
	v_cvt_pk_f32_fp8_sdwa v[50:51], v102 src0_sel:WORD_1
	v_cvt_pk_f32_fp8_e32 v[52:53], v103
	v_cvt_pk_f32_fp8_sdwa v[54:55], v103 src0_sel:WORD_1
	v_pk_fma_f32 v[24:25], v[40:41], v[226:227], v[24:25] op_sel_hi:[1,0,1]
	v_pk_fma_f32 v[26:27], v[42:43], v[226:227], v[26:27] op_sel_hi:[1,0,1]
	v_pk_fma_f32 v[28:29], v[44:45], v[226:227], v[28:29] op_sel_hi:[1,0,1]
	v_pk_fma_f32 v[30:31], v[46:47], v[226:227], v[30:31] op_sel_hi:[1,0,1]
	v_pk_fma_f32 v[32:33], v[48:49], v[226:227], v[32:33] op_sel_hi:[1,0,1]
	v_pk_fma_f32 v[34:35], v[50:51], v[226:227], v[34:35] op_sel_hi:[1,0,1]
	v_pk_fma_f32 v[36:37], v[52:53], v[226:227], v[36:37] op_sel_hi:[1,0,1]
	v_pk_fma_f32 v[38:39], v[54:55], v[226:227], v[38:39] op_sel_hi:[1,0,1]
	v_cvt_pk_f32_fp8_e32 v[40:41], v104
	v_cvt_pk_f32_fp8_sdwa v[42:43], v104 src0_sel:WORD_1
	v_cvt_pk_f32_fp8_e32 v[44:45], v105
	v_cvt_pk_f32_fp8_sdwa v[46:47], v105 src0_sel:WORD_1
	v_cvt_pk_f32_fp8_e32 v[48:49], v106
	v_cvt_pk_f32_fp8_sdwa v[50:51], v106 src0_sel:WORD_1
	v_cvt_pk_f32_fp8_e32 v[52:53], v107
	v_cvt_pk_f32_fp8_sdwa v[54:55], v107 src0_sel:WORD_1
	v_pk_fma_f32 v[24:25], v[40:41], v[228:229], v[24:25] op_sel_hi:[1,0,1]
	v_pk_fma_f32 v[26:27], v[42:43], v[228:229], v[26:27] op_sel_hi:[1,0,1]
	v_pk_fma_f32 v[28:29], v[44:45], v[228:229], v[28:29] op_sel_hi:[1,0,1]
	v_pk_fma_f32 v[30:31], v[46:47], v[228:229], v[30:31] op_sel_hi:[1,0,1]
	v_pk_fma_f32 v[32:33], v[48:49], v[228:229], v[32:33] op_sel_hi:[1,0,1]
	v_pk_fma_f32 v[34:35], v[50:51], v[228:229], v[34:35] op_sel_hi:[1,0,1]
	v_pk_fma_f32 v[36:37], v[52:53], v[228:229], v[36:37] op_sel_hi:[1,0,1]
	v_pk_fma_f32 v[38:39], v[54:55], v[228:229], v[38:39] op_sel_hi:[1,0,1]
	v_cvt_pk_f32_fp8_e32 v[40:41], v108
	v_cvt_pk_f32_fp8_sdwa v[42:43], v108 src0_sel:WORD_1
	v_cvt_pk_f32_fp8_e32 v[44:45], v109
	v_cvt_pk_f32_fp8_sdwa v[46:47], v109 src0_sel:WORD_1
	v_cvt_pk_f32_fp8_e32 v[48:49], v110
	v_cvt_pk_f32_fp8_sdwa v[50:51], v110 src0_sel:WORD_1
	v_cvt_pk_f32_fp8_e32 v[52:53], v111
	v_cvt_pk_f32_fp8_sdwa v[54:55], v111 src0_sel:WORD_1
	v_pk_fma_f32 v[24:25], v[40:41], v[230:231], v[24:25] op_sel_hi:[1,0,1]
	v_pk_fma_f32 v[26:27], v[42:43], v[230:231], v[26:27] op_sel_hi:[1,0,1]
	v_pk_fma_f32 v[28:29], v[44:45], v[230:231], v[28:29] op_sel_hi:[1,0,1]
	v_pk_fma_f32 v[30:31], v[46:47], v[230:231], v[30:31] op_sel_hi:[1,0,1]
	v_pk_fma_f32 v[32:33], v[48:49], v[230:231], v[32:33] op_sel_hi:[1,0,1]
	v_pk_fma_f32 v[34:35], v[50:51], v[230:231], v[34:35] op_sel_hi:[1,0,1]
	v_pk_fma_f32 v[36:37], v[52:53], v[230:231], v[36:37] op_sel_hi:[1,0,1]
	v_pk_fma_f32 v[38:39], v[54:55], v[230:231], v[38:39] op_sel_hi:[1,0,1]
	v_cvt_pk_f32_fp8_e32 v[40:41], v112
	v_cvt_pk_f32_fp8_sdwa v[42:43], v112 src0_sel:WORD_1
	v_cvt_pk_f32_fp8_e32 v[44:45], v113
	v_cvt_pk_f32_fp8_sdwa v[46:47], v113 src0_sel:WORD_1
	v_cvt_pk_f32_fp8_e32 v[48:49], v114
	v_cvt_pk_f32_fp8_sdwa v[50:51], v114 src0_sel:WORD_1
	v_cvt_pk_f32_fp8_e32 v[52:53], v115
	v_cvt_pk_f32_fp8_sdwa v[54:55], v115 src0_sel:WORD_1
	v_pk_fma_f32 v[24:25], v[40:41], v[232:233], v[24:25] op_sel_hi:[1,0,1]
	v_pk_fma_f32 v[26:27], v[42:43], v[232:233], v[26:27] op_sel_hi:[1,0,1]
	v_pk_fma_f32 v[28:29], v[44:45], v[232:233], v[28:29] op_sel_hi:[1,0,1]
	v_pk_fma_f32 v[30:31], v[46:47], v[232:233], v[30:31] op_sel_hi:[1,0,1]
	v_pk_fma_f32 v[32:33], v[48:49], v[232:233], v[32:33] op_sel_hi:[1,0,1]
	v_pk_fma_f32 v[34:35], v[50:51], v[232:233], v[34:35] op_sel_hi:[1,0,1]
	v_pk_fma_f32 v[36:37], v[52:53], v[232:233], v[36:37] op_sel_hi:[1,0,1]
	v_pk_fma_f32 v[38:39], v[54:55], v[232:233], v[38:39] op_sel_hi:[1,0,1]
	v_cvt_pk_f32_fp8_e32 v[40:41], v116
	v_cvt_pk_f32_fp8_sdwa v[42:43], v116 src0_sel:WORD_1
	v_cvt_pk_f32_fp8_e32 v[44:45], v117
	v_cvt_pk_f32_fp8_sdwa v[46:47], v117 src0_sel:WORD_1
	v_cvt_pk_f32_fp8_e32 v[48:49], v118
	v_cvt_pk_f32_fp8_sdwa v[50:51], v118 src0_sel:WORD_1
	v_cvt_pk_f32_fp8_e32 v[52:53], v119
	v_cvt_pk_f32_fp8_sdwa v[54:55], v119 src0_sel:WORD_1
	v_pk_fma_f32 v[24:25], v[40:41], v[234:235], v[24:25] op_sel_hi:[1,0,1]
	v_pk_fma_f32 v[26:27], v[42:43], v[234:235], v[26:27] op_sel_hi:[1,0,1]
	v_pk_fma_f32 v[28:29], v[44:45], v[234:235], v[28:29] op_sel_hi:[1,0,1]
	v_pk_fma_f32 v[30:31], v[46:47], v[234:235], v[30:31] op_sel_hi:[1,0,1]
	v_pk_fma_f32 v[32:33], v[48:49], v[234:235], v[32:33] op_sel_hi:[1,0,1]
	v_pk_fma_f32 v[34:35], v[50:51], v[234:235], v[34:35] op_sel_hi:[1,0,1]
	v_pk_fma_f32 v[36:37], v[52:53], v[234:235], v[36:37] op_sel_hi:[1,0,1]
	v_pk_fma_f32 v[38:39], v[54:55], v[234:235], v[38:39] op_sel_hi:[1,0,1]
	v_cvt_pk_f32_fp8_e32 v[40:41], v120
	v_cvt_pk_f32_fp8_sdwa v[42:43], v120 src0_sel:WORD_1
	v_cvt_pk_f32_fp8_e32 v[44:45], v121
	v_cvt_pk_f32_fp8_sdwa v[46:47], v121 src0_sel:WORD_1
	v_cvt_pk_f32_fp8_e32 v[48:49], v122
	v_cvt_pk_f32_fp8_sdwa v[50:51], v122 src0_sel:WORD_1
	v_cvt_pk_f32_fp8_e32 v[52:53], v123
	v_cvt_pk_f32_fp8_sdwa v[54:55], v123 src0_sel:WORD_1
	v_pk_fma_f32 v[24:25], v[40:41], v[236:237], v[24:25] op_sel_hi:[1,0,1]
	v_pk_fma_f32 v[26:27], v[42:43], v[236:237], v[26:27] op_sel_hi:[1,0,1]
	v_pk_fma_f32 v[28:29], v[44:45], v[236:237], v[28:29] op_sel_hi:[1,0,1]
	v_pk_fma_f32 v[30:31], v[46:47], v[236:237], v[30:31] op_sel_hi:[1,0,1]
	v_pk_fma_f32 v[32:33], v[48:49], v[236:237], v[32:33] op_sel_hi:[1,0,1]
	v_pk_fma_f32 v[34:35], v[50:51], v[236:237], v[34:35] op_sel_hi:[1,0,1]
	v_pk_fma_f32 v[36:37], v[52:53], v[236:237], v[36:37] op_sel_hi:[1,0,1]
	v_pk_fma_f32 v[38:39], v[54:55], v[236:237], v[38:39] op_sel_hi:[1,0,1]
	v_cvt_pk_f32_fp8_e32 v[40:41], v124
	v_cvt_pk_f32_fp8_sdwa v[42:43], v124 src0_sel:WORD_1
	v_cvt_pk_f32_fp8_e32 v[44:45], v125
	v_cvt_pk_f32_fp8_sdwa v[46:47], v125 src0_sel:WORD_1
	v_cvt_pk_f32_fp8_e32 v[48:49], v126
	v_cvt_pk_f32_fp8_sdwa v[50:51], v126 src0_sel:WORD_1
	v_cvt_pk_f32_fp8_e32 v[52:53], v127
	v_cvt_pk_f32_fp8_sdwa v[54:55], v127 src0_sel:WORD_1
	v_pk_fma_f32 v[24:25], v[40:41], v[238:239], v[24:25] op_sel_hi:[1,0,1]
	v_pk_fma_f32 v[26:27], v[42:43], v[238:239], v[26:27] op_sel_hi:[1,0,1]
	v_pk_fma_f32 v[28:29], v[44:45], v[238:239], v[28:29] op_sel_hi:[1,0,1]
	v_pk_fma_f32 v[30:31], v[46:47], v[238:239], v[30:31] op_sel_hi:[1,0,1]
	v_pk_fma_f32 v[32:33], v[48:49], v[238:239], v[32:33] op_sel_hi:[1,0,1]
	v_pk_fma_f32 v[34:35], v[50:51], v[238:239], v[34:35] op_sel_hi:[1,0,1]
	v_pk_fma_f32 v[36:37], v[52:53], v[238:239], v[36:37] op_sel_hi:[1,0,1]
	v_pk_fma_f32 v[38:39], v[54:55], v[238:239], v[38:39] op_sel_hi:[1,0,1]
	ds_write_b128 v5, v[24:27]
	ds_write_b128 v5, v[28:31] offset:16
	ds_write_b128 v5, v[32:35] offset:32
	ds_write_b128 v5, v[36:39] offset:48
	ds_read_b64 v[40:41], v6
	ds_read_b64 v[42:43], v6 offset:512
	ds_read_b64 v[44:45], v6 offset:1024
	ds_read_b64 v[46:47], v6 offset:1536
	ds_read_b64 v[48:49], v6 offset:2048
	ds_read_b64 v[50:51], v6 offset:2560
	ds_read_b64 v[52:53], v6 offset:3072
	ds_read_b64 v[54:55], v6 offset:3584
	s_waitcnt lgkmcnt(6)
	v_pk_add_f32 v[40:41], v[40:41], v[42:43]
	s_waitcnt lgkmcnt(5)
	v_pk_add_f32 v[40:41], v[40:41], v[44:45]
	s_waitcnt lgkmcnt(4)
	v_pk_add_f32 v[40:41], v[40:41], v[46:47]
	s_waitcnt lgkmcnt(3)
	v_pk_add_f32 v[40:41], v[40:41], v[48:49]
	s_waitcnt lgkmcnt(2)
	v_pk_add_f32 v[40:41], v[40:41], v[50:51]
	s_waitcnt lgkmcnt(1)
	v_pk_add_f32 v[40:41], v[40:41], v[52:53]
	s_waitcnt lgkmcnt(0)
	v_pk_add_f32 v[40:41], v[40:41], v[54:55]
	v_pk_fma_f32 v[40:41], v[18:19], s[24:25], v[40:41] op_sel_hi:[1,0,1]
	s_lshl_b32 s30, s22, 12
	s_add_u32 s66, s16, s30
	s_addc_u32 s67, s17, 0
	global_store_dwordx2 v2, v[40:41], s[66:67]
	v_mov_b32_e32 v12, v14
	v_mov_b32_e32 v13, v15
	v_mov_b32_e32 v18, v20
	v_mov_b32_e32 v19, v21
	s_add_u32 s22, s22, s12
	s_cmp_ge_u32 s22, 0x8000
	s_cbranch_scc1 .Lgv_done
	s_waitcnt vmcnt(16)
	v_mov_b32_e32 v8, v10
	v_mov_b32_e32 v9, v11
	v_mov_b32_e32 v14, v16
	v_mov_b32_e32 v15, v17
	v_mov_b32_e32 v20, v22
	v_mov_b32_e32 v21, v23
	ds_bpermute_b32 v192, v4, v8
	ds_bpermute_b32 v193, v4, v8 offset:32
	ds_bpermute_b32 v194, v4, v8 offset:64
	ds_bpermute_b32 v195, v4, v8 offset:96
	ds_bpermute_b32 v196, v4, v8 offset:128
	ds_bpermute_b32 v197, v4, v8 offset:160
	ds_bpermute_b32 v198, v4, v8 offset:192
	ds_bpermute_b32 v199, v4, v8 offset:224
	ds_bpermute_b32 v200, v4, v9
	ds_bpermute_b32 v201, v4, v9 offset:32
	ds_bpermute_b32 v202, v4, v9 offset:64
	ds_bpermute_b32 v203, v4, v9 offset:96
	ds_bpermute_b32 v204, v4, v9 offset:128
	ds_bpermute_b32 v205, v4, v9 offset:160
	ds_bpermute_b32 v206, v4, v9 offset:192
	ds_bpermute_b32 v207, v4, v9 offset:224
	s_mov_b32 s31, s12
	s_add_u32 s26, s22, s31
	s_min_u32 s26, s26, 0x7fff
	s_mov_b32 s42, s26
	s_mul_i32 s31, s12, 2
	s_add_u32 s26, s22, s31
	s_min_u32 s26, s26, 0x7fff
	s_lshl_b32 s30, s26, 9
	s_add_u32 s40, s18, s30
	s_addc_u32 s41, s19, 0
	global_load_dword v10, v1, s[40:41]
	global_load_dword v11, v1, s[40:41] offset:256
	s_add_u32 s64, s20, s30
	s_addc_u32 s65, s21, 0
	global_load_dword v16, v1, s[64:65]
	global_load_dword v17, v1, s[64:65] offset:256
	s_lshl_b32 s30, s26, 12
	s_add_u32 s66, s16, s30
	s_addc_u32 s67, s17, 0
	global_load_dwordx2 v[22:23], v2, s[66:67]
	ds_bpermute_b32 v208, v4, v12
	ds_bpermute_b32 v210, v4, v12 offset:32
	ds_bpermute_b32 v212, v4, v12 offset:64
	ds_bpermute_b32 v214, v4, v12 offset:96
	ds_bpermute_b32 v216, v4, v12 offset:128
	ds_bpermute_b32 v218, v4, v12 offset:160
	ds_bpermute_b32 v220, v4, v12 offset:192
	ds_bpermute_b32 v222, v4, v12 offset:224
	ds_bpermute_b32 v224, v4, v13
	ds_bpermute_b32 v226, v4, v13 offset:32
	ds_bpermute_b32 v228, v4, v13 offset:64
	ds_bpermute_b32 v230, v4, v13 offset:96
	ds_bpermute_b32 v232, v4, v13 offset:128
	ds_bpermute_b32 v234, v4, v13 offset:160
	ds_bpermute_b32 v236, v4, v13 offset:192
	ds_bpermute_b32 v238, v4, v13 offset:224
	s_waitcnt lgkmcnt(0)
	v_lshl_add_u32 v192, v192, 7, v3
	global_load_dwordx4 v[64:67], v192, s[14:15]
	v_lshl_add_u32 v193, v193, 7, v3
	global_load_dwordx4 v[68:71], v193, s[14:15]
	v_lshl_add_u32 v194, v194, 7, v3
	global_load_dwordx4 v[72:75], v194, s[14:15]
	v_lshl_add_u32 v195, v195, 7, v3
	global_load_dwordx4 v[76:79], v195, s[14:15]
	v_lshl_add_u32 v196, v196, 7, v3
	global_load_dwordx4 v[80:83], v196, s[14:15]
	v_lshl_add_u32 v197, v197, 7, v3
	global_load_dwordx4 v[84:87], v197, s[14:15]
	v_lshl_add_u32 v198, v198, 7, v3
	global_load_dwordx4 v[88:91], v198, s[14:15]
	v_lshl_add_u32 v199, v199, 7, v3
	global_load_dwordx4 v[92:95], v199, s[14:15]
	v_lshl_add_u32 v200, v200, 7, v3
	global_load_dwordx4 v[96:99], v200, s[14:15]
	v_lshl_add_u32 v201, v201, 7, v3
	global_load_dwordx4 v[100:103], v201, s[14:15]
	v_lshl_add_u32 v202, v202, 7, v3
	global_load_dwordx4 v[104:107], v202, s[14:15]
	v_lshl_add_u32 v203, v203, 7, v3
	global_load_dwordx4 v[108:111], v203, s[14:15]
	v_lshl_add_u32 v204, v204, 7, v3
	global_load_dwordx4 v[112:115], v204, s[14:15]
	v_lshl_add_u32 v205, v205, 7, v3
	global_load_dwordx4 v[116:119], v205, s[14:15]
	v_lshl_add_u32 v206, v206, 7, v3
	global_load_dwordx4 v[120:123], v206, s[14:15]
	v_lshl_add_u32 v207, v207, 7, v3
	global_load_dwordx4 v[124:127], v207, s[14:15]
	s_waitcnt vmcnt(21)
	v_cvt_pk_f32_fp8_e32 v[40:41], v128
	v_cvt_pk_f32_fp8_sdwa v[42:43], v128 src0_sel:WORD_1
	v_cvt_pk_f32_fp8_e32 v[44:45], v129
	v_cvt_pk_f32_fp8_sdwa v[46:47], v129 src0_sel:WORD_1
	v_cvt_pk_f32_fp8_e32 v[48:49], v130
	v_cvt_pk_f32_fp8_sdwa v[50:51], v130 src0_sel:WORD_1
	v_cvt_pk_f32_fp8_e32 v[52:53], v131
	v_cvt_pk_f32_fp8_sdwa v[54:55], v131 src0_sel:WORD_1
	v_pk_mul_f32 v[24:25], v[40:41], v[208:209] op_sel_hi:[1,0]
	v_pk_mul_f32 v[26:27], v[42:43], v[208:209] op_sel_hi:[1,0]
	v_pk_mul_f32 v[28:29], v[44:45], v[208:209] op_sel_hi:[1,0]
	v_pk_mul_f32 v[30:31], v[46:47], v[208:209] op_sel_hi:[1,0]
	v_pk_mul_f32 v[32:33], v[48:49], v[208:209] op_sel_hi:[1,0]
	v_pk_mul_f32 v[34:35], v[50:51], v[208:209] op_sel_hi:[1,0]
	v_pk_mul_f32 v[36:37], v[52:53], v[208:209] op_sel_hi:[1,0]
	v_pk_mul_f32 v[38:39], v[54:55], v[208:209] op_sel_hi:[1,0]
	v_cvt_pk_f32_fp8_e32 v[40:41], v132
	v_cvt_pk_f32_fp8_sdwa v[42:43], v132 src0_sel:WORD_1
	v_cvt_pk_f32_fp8_e32 v[44:45], v133
	v_cvt_pk_f32_fp8_sdwa v[46:47], v133 src0_sel:WORD_1
	v_cvt_pk_f32_fp8_e32 v[48:49], v134
	v_cvt_pk_f32_fp8_sdwa v[50:51], v134 src0_sel:WORD_1
	v_cvt_pk_f32_fp8_e32 v[52:53], v135
	v_cvt_pk_f32_fp8_sdwa v[54:55], v135 src0_sel:WORD_1
	v_pk_fma_f32 v[24:25], v[40:41], v[210:211], v[24:25] op_sel_hi:[1,0,1]
	v_pk_fma_f32 v[26:27], v[42:43], v[210:211], v[26:27] op_sel_hi:[1,0,1]
	v_pk_fma_f32 v[28:29], v[44:45], v[210:211], v[28:29] op_sel_hi:[1,0,1]
	v_pk_fma_f32 v[30:31], v[46:47], v[210:211], v[30:31] op_sel_hi:[1,0,1]
	v_pk_fma_f32 v[32:33], v[48:49], v[210:211], v[32:33] op_sel_hi:[1,0,1]
	v_pk_fma_f32 v[34:35], v[50:51], v[210:211], v[34:35] op_sel_hi:[1,0,1]
	v_pk_fma_f32 v[36:37], v[52:53], v[210:211], v[36:37] op_sel_hi:[1,0,1]
	v_pk_fma_f32 v[38:39], v[54:55], v[210:211], v[38:39] op_sel_hi:[1,0,1]
	v_cvt_pk_f32_fp8_e32 v[40:41], v136
	v_cvt_pk_f32_fp8_sdwa v[42:43], v136 src0_sel:WORD_1
	v_cvt_pk_f32_fp8_e32 v[44:45], v137
	v_cvt_pk_f32_fp8_sdwa v[46:47], v137 src0_sel:WORD_1
	v_cvt_pk_f32_fp8_e32 v[48:49], v138
	v_cvt_pk_f32_fp8_sdwa v[50:51], v138 src0_sel:WORD_1
	v_cvt_pk_f32_fp8_e32 v[52:53], v139
	v_cvt_pk_f32_fp8_sdwa v[54:55], v139 src0_sel:WORD_1
	v_pk_fma_f32 v[24:25], v[40:41], v[212:213], v[24:25] op_sel_hi:[1,0,1]
	v_pk_fma_f32 v[26:27], v[42:43], v[212:213], v[26:27] op_sel_hi:[1,0,1]
	v_pk_fma_f32 v[28:29], v[44:45], v[212:213], v[28:29] op_sel_hi:[1,0,1]
	v_pk_fma_f32 v[30:31], v[46:47], v[212:213], v[30:31] op_sel_hi:[1,0,1]
	v_pk_fma_f32 v[32:33], v[48:49], v[212:213], v[32:33] op_sel_hi:[1,0,1]
	v_pk_fma_f32 v[34:35], v[50:51], v[212:213], v[34:35] op_sel_hi:[1,0,1]
	v_pk_fma_f32 v[36:37], v[52:53], v[212:213], v[36:37] op_sel_hi:[1,0,1]
	v_pk_fma_f32 v[38:39], v[54:55], v[212:213], v[38:39] op_sel_hi:[1,0,1]
	v_cvt_pk_f32_fp8_e32 v[40:41], v140
	v_cvt_pk_f32_fp8_sdwa v[42:43], v140 src0_sel:WORD_1
	v_cvt_pk_f32_fp8_e32 v[44:45], v141
	v_cvt_pk_f32_fp8_sdwa v[46:47], v141 src0_sel:WORD_1
	v_cvt_pk_f32_fp8_e32 v[48:49], v142
	v_cvt_pk_f32_fp8_sdwa v[50:51], v142 src0_sel:WORD_1
	v_cvt_pk_f32_fp8_e32 v[52:53], v143
	v_cvt_pk_f32_fp8_sdwa v[54:55], v143 src0_sel:WORD_1
	v_pk_fma_f32 v[24:25], v[40:41], v[214:215], v[24:25] op_sel_hi:[1,0,1]
	v_pk_fma_f32 v[26:27], v[42:43], v[214:215], v[26:27] op_sel_hi:[1,0,1]
	v_pk_fma_f32 v[28:29], v[44:45], v[214:215], v[28:29] op_sel_hi:[1,0,1]
	v_pk_fma_f32 v[30:31], v[46:47], v[214:215], v[30:31] op_sel_hi:[1,0,1]
	v_pk_fma_f32 v[32:33], v[48:49], v[214:215], v[32:33] op_sel_hi:[1,0,1]
	v_pk_fma_f32 v[34:35], v[50:51], v[214:215], v[34:35] op_sel_hi:[1,0,1]
	v_pk_fma_f32 v[36:37], v[52:53], v[214:215], v[36:37] op_sel_hi:[1,0,1]
	v_pk_fma_f32 v[38:39], v[54:55], v[214:215], v[38:39] op_sel_hi:[1,0,1]
	v_cvt_pk_f32_fp8_e32 v[40:41], v144
	v_cvt_pk_f32_fp8_sdwa v[42:43], v144 src0_sel:WORD_1
	v_cvt_pk_f32_fp8_e32 v[44:45], v145
	v_cvt_pk_f32_fp8_sdwa v[46:47], v145 src0_sel:WORD_1
	v_cvt_pk_f32_fp8_e32 v[48:49], v146
	v_cvt_pk_f32_fp8_sdwa v[50:51], v146 src0_sel:WORD_1
	v_cvt_pk_f32_fp8_e32 v[52:53], v147
	v_cvt_pk_f32_fp8_sdwa v[54:55], v147 src0_sel:WORD_1
	v_pk_fma_f32 v[24:25], v[40:41], v[216:217], v[24:25] op_sel_hi:[1,0,1]
	v_pk_fma_f32 v[26:27], v[42:43], v[216:217], v[26:27] op_sel_hi:[1,0,1]
	v_pk_fma_f32 v[28:29], v[44:45], v[216:217], v[28:29] op_sel_hi:[1,0,1]
	v_pk_fma_f32 v[30:31], v[46:47], v[216:217], v[30:31] op_sel_hi:[1,0,1]
	v_pk_fma_f32 v[32:33], v[48:49], v[216:217], v[32:33] op_sel_hi:[1,0,1]
	v_pk_fma_f32 v[34:35], v[50:51], v[216:217], v[34:35] op_sel_hi:[1,0,1]
	v_pk_fma_f32 v[36:37], v[52:53], v[216:217], v[36:37] op_sel_hi:[1,0,1]
	v_pk_fma_f32 v[38:39], v[54:55], v[216:217], v[38:39] op_sel_hi:[1,0,1]
	v_cvt_pk_f32_fp8_e32 v[40:41], v148
	v_cvt_pk_f32_fp8_sdwa v[42:43], v148 src0_sel:WORD_1
	v_cvt_pk_f32_fp8_e32 v[44:45], v149
	v_cvt_pk_f32_fp8_sdwa v[46:47], v149 src0_sel:WORD_1
	v_cvt_pk_f32_fp8_e32 v[48:49], v150
	v_cvt_pk_f32_fp8_sdwa v[50:51], v150 src0_sel:WORD_1
	v_cvt_pk_f32_fp8_e32 v[52:53], v151
	v_cvt_pk_f32_fp8_sdwa v[54:55], v151 src0_sel:WORD_1
	v_pk_fma_f32 v[24:25], v[40:41], v[218:219], v[24:25] op_sel_hi:[1,0,1]
	v_pk_fma_f32 v[26:27], v[42:43], v[218:219], v[26:27] op_sel_hi:[1,0,1]
	v_pk_fma_f32 v[28:29], v[44:45], v[218:219], v[28:29] op_sel_hi:[1,0,1]
	v_pk_fma_f32 v[30:31], v[46:47], v[218:219], v[30:31] op_sel_hi:[1,0,1]
	v_pk_fma_f32 v[32:33], v[48:49], v[218:219], v[32:33] op_sel_hi:[1,0,1]
	v_pk_fma_f32 v[34:35], v[50:51], v[218:219], v[34:35] op_sel_hi:[1,0,1]
	v_pk_fma_f32 v[36:37], v[52:53], v[218:219], v[36:37] op_sel_hi:[1,0,1]
	v_pk_fma_f32 v[38:39], v[54:55], v[218:219], v[38:39] op_sel_hi:[1,0,1]
	v_cvt_pk_f32_fp8_e32 v[40:41], v152
	v_cvt_pk_f32_fp8_sdwa v[42:43], v152 src0_sel:WORD_1
	v_cvt_pk_f32_fp8_e32 v[44:45], v153
	v_cvt_pk_f32_fp8_sdwa v[46:47], v153 src0_sel:WORD_1
	v_cvt_pk_f32_fp8_e32 v[48:49], v154
	v_cvt_pk_f32_fp8_sdwa v[50:51], v154 src0_sel:WORD_1
	v_cvt_pk_f32_fp8_e32 v[52:53], v155
	v_cvt_pk_f32_fp8_sdwa v[54:55], v155 src0_sel:WORD_1
	v_pk_fma_f32 v[24:25], v[40:41], v[220:221], v[24:25] op_sel_hi:[1,0,1]
	v_pk_fma_f32 v[26:27], v[42:43], v[220:221], v[26:27] op_sel_hi:[1,0,1]
	v_pk_fma_f32 v[28:29], v[44:45], v[220:221], v[28:29] op_sel_hi:[1,0,1]
	v_pk_fma_f32 v[30:31], v[46:47], v[220:221], v[30:31] op_sel_hi:[1,0,1]
	v_pk_fma_f32 v[32:33], v[48:49], v[220:221], v[32:33] op_sel_hi:[1,0,1]
	v_pk_fma_f32 v[34:35], v[50:51], v[220:221], v[34:35] op_sel_hi:[1,0,1]
	v_pk_fma_f32 v[36:37], v[52:53], v[220:221], v[36:37] op_sel_hi:[1,0,1]
	v_pk_fma_f32 v[38:39], v[54:55], v[220:221], v[38:39] op_sel_hi:[1,0,1]
	v_cvt_pk_f32_fp8_e32 v[40:41], v156
	v_cvt_pk_f32_fp8_sdwa v[42:43], v156 src0_sel:WORD_1
	v_cvt_pk_f32_fp8_e32 v[44:45], v157
	v_cvt_pk_f32_fp8_sdwa v[46:47], v157 src0_sel:WORD_1
	v_cvt_pk_f32_fp8_e32 v[48:49], v158
	v_cvt_pk_f32_fp8_sdwa v[50:51], v158 src0_sel:WORD_1
	v_cvt_pk_f32_fp8_e32 v[52:53], v159
	v_cvt_pk_f32_fp8_sdwa v[54:55], v159 src0_sel:WORD_1
	v_pk_fma_f32 v[24:25], v[40:41], v[222:223], v[24:25] op_sel_hi:[1,0,1]
	v_pk_fma_f32 v[26:27], v[42:43], v[222:223], v[26:27] op_sel_hi:[1,0,1]
	v_pk_fma_f32 v[28:29], v[44:45], v[222:223], v[28:29] op_sel_hi:[1,0,1]
	v_pk_fma_f32 v[30:31], v[46:47], v[222:223], v[30:31] op_sel_hi:[1,0,1]
	v_pk_fma_f32 v[32:33], v[48:49], v[222:223], v[32:33] op_sel_hi:[1,0,1]
	v_pk_fma_f32 v[34:35], v[50:51], v[222:223], v[34:35] op_sel_hi:[1,0,1]
	v_pk_fma_f32 v[36:37], v[52:53], v[222:223], v[36:37] op_sel_hi:[1,0,1]
	v_pk_fma_f32 v[38:39], v[54:55], v[222:223], v[38:39] op_sel_hi:[1,0,1]
	v_cvt_pk_f32_fp8_e32 v[40:41], v160
	v_cvt_pk_f32_fp8_sdwa v[42:43], v160 src0_sel:WORD_1
	v_cvt_pk_f32_fp8_e32 v[44:45], v161
	v_cvt_pk_f32_fp8_sdwa v[46:47], v161 src0_sel:WORD_1
	v_cvt_pk_f32_fp8_e32 v[48:49], v162
	v_cvt_pk_f32_fp8_sdwa v[50:51], v162 src0_sel:WORD_1
	v_cvt_pk_f32_fp8_e32 v[52:53], v163
	v_cvt_pk_f32_fp8_sdwa v[54:55], v163 src0_sel:WORD_1
	v_pk_fma_f32 v[24:25], v[40:41], v[224:225], v[24:25] op_sel_hi:[1,0,1]
	v_pk_fma_f32 v[26:27], v[42:43], v[224:225], v[26:27] op_sel_hi:[1,0,1]
	v_pk_fma_f32 v[28:29], v[44:45], v[224:225], v[28:29] op_sel_hi:[1,0,1]
	v_pk_fma_f32 v[30:31], v[46:47], v[224:225], v[30:31] op_sel_hi:[1,0,1]
	v_pk_fma_f32 v[32:33], v[48:49], v[224:225], v[32:33] op_sel_hi:[1,0,1]
	v_pk_fma_f32 v[34:35], v[50:51], v[224:225], v[34:35] op_sel_hi:[1,0,1]
	v_pk_fma_f32 v[36:37], v[52:53], v[224:225], v[36:37] op_sel_hi:[1,0,1]
	v_pk_fma_f32 v[38:39], v[54:55], v[224:225], v[38:39] op_sel_hi:[1,0,1]
	v_cvt_pk_f32_fp8_e32 v[40:41], v164
	v_cvt_pk_f32_fp8_sdwa v[42:43], v164 src0_sel:WORD_1
	v_cvt_pk_f32_fp8_e32 v[44:45], v165
	v_cvt_pk_f32_fp8_sdwa v[46:47], v165 src0_sel:WORD_1
	v_cvt_pk_f32_fp8_e32 v[48:49], v166
	v_cvt_pk_f32_fp8_sdwa v[50:51], v166 src0_sel:WORD_1
	v_cvt_pk_f32_fp8_e32 v[52:53], v167
	v_cvt_pk_f32_fp8_sdwa v[54:55], v167 src0_sel:WORD_1
	v_pk_fma_f32 v[24:25], v[40:41], v[226:227], v[24:25] op_sel_hi:[1,0,1]
	v_pk_fma_f32 v[26:27], v[42:43], v[226:227], v[26:27] op_sel_hi:[1,0,1]
	v_pk_fma_f32 v[28:29], v[44:45], v[226:227], v[28:29] op_sel_hi:[1,0,1]
	v_pk_fma_f32 v[30:31], v[46:47], v[226:227], v[30:31] op_sel_hi:[1,0,1]
	v_pk_fma_f32 v[32:33], v[48:49], v[226:227], v[32:33] op_sel_hi:[1,0,1]
	v_pk_fma_f32 v[34:35], v[50:51], v[226:227], v[34:35] op_sel_hi:[1,0,1]
	v_pk_fma_f32 v[36:37], v[52:53], v[226:227], v[36:37] op_sel_hi:[1,0,1]
	v_pk_fma_f32 v[38:39], v[54:55], v[226:227], v[38:39] op_sel_hi:[1,0,1]
	v_cvt_pk_f32_fp8_e32 v[40:41], v168
	v_cvt_pk_f32_fp8_sdwa v[42:43], v168 src0_sel:WORD_1
	v_cvt_pk_f32_fp8_e32 v[44:45], v169
	v_cvt_pk_f32_fp8_sdwa v[46:47], v169 src0_sel:WORD_1
	v_cvt_pk_f32_fp8_e32 v[48:49], v170
	v_cvt_pk_f32_fp8_sdwa v[50:51], v170 src0_sel:WORD_1
	v_cvt_pk_f32_fp8_e32 v[52:53], v171
	v_cvt_pk_f32_fp8_sdwa v[54:55], v171 src0_sel:WORD_1
	v_pk_fma_f32 v[24:25], v[40:41], v[228:229], v[24:25] op_sel_hi:[1,0,1]
	v_pk_fma_f32 v[26:27], v[42:43], v[228:229], v[26:27] op_sel_hi:[1,0,1]
	v_pk_fma_f32 v[28:29], v[44:45], v[228:229], v[28:29] op_sel_hi:[1,0,1]
	v_pk_fma_f32 v[30:31], v[46:47], v[228:229], v[30:31] op_sel_hi:[1,0,1]
	v_pk_fma_f32 v[32:33], v[48:49], v[228:229], v[32:33] op_sel_hi:[1,0,1]
	v_pk_fma_f32 v[34:35], v[50:51], v[228:229], v[34:35] op_sel_hi:[1,0,1]
	v_pk_fma_f32 v[36:37], v[52:53], v[228:229], v[36:37] op_sel_hi:[1,0,1]
	v_pk_fma_f32 v[38:39], v[54:55], v[228:229], v[38:39] op_sel_hi:[1,0,1]
	v_cvt_pk_f32_fp8_e32 v[40:41], v172
	v_cvt_pk_f32_fp8_sdwa v[42:43], v172 src0_sel:WORD_1
	v_cvt_pk_f32_fp8_e32 v[44:45], v173
	v_cvt_pk_f32_fp8_sdwa v[46:47], v173 src0_sel:WORD_1
	v_cvt_pk_f32_fp8_e32 v[48:49], v174
	v_cvt_pk_f32_fp8_sdwa v[50:51], v174 src0_sel:WORD_1
	v_cvt_pk_f32_fp8_e32 v[52:53], v175
	v_cvt_pk_f32_fp8_sdwa v[54:55], v175 src0_sel:WORD_1
	v_pk_fma_f32 v[24:25], v[40:41], v[230:231], v[24:25] op_sel_hi:[1,0,1]
	v_pk_fma_f32 v[26:27], v[42:43], v[230:231], v[26:27] op_sel_hi:[1,0,1]
	v_pk_fma_f32 v[28:29], v[44:45], v[230:231], v[28:29] op_sel_hi:[1,0,1]
	v_pk_fma_f32 v[30:31], v[46:47], v[230:231], v[30:31] op_sel_hi:[1,0,1]
	v_pk_fma_f32 v[32:33], v[48:49], v[230:231], v[32:33] op_sel_hi:[1,0,1]
	v_pk_fma_f32 v[34:35], v[50:51], v[230:231], v[34:35] op_sel_hi:[1,0,1]
	v_pk_fma_f32 v[36:37], v[52:53], v[230:231], v[36:37] op_sel_hi:[1,0,1]
	v_pk_fma_f32 v[38:39], v[54:55], v[230:231], v[38:39] op_sel_hi:[1,0,1]
	v_cvt_pk_f32_fp8_e32 v[40:41], v176
	v_cvt_pk_f32_fp8_sdwa v[42:43], v176 src0_sel:WORD_1
	v_cvt_pk_f32_fp8_e32 v[44:45], v177
	v_cvt_pk_f32_fp8_sdwa v[46:47], v177 src0_sel:WORD_1
	v_cvt_pk_f32_fp8_e32 v[48:49], v178
	v_cvt_pk_f32_fp8_sdwa v[50:51], v178 src0_sel:WORD_1
	v_cvt_pk_f32_fp8_e32 v[52:53], v179
	v_cvt_pk_f32_fp8_sdwa v[54:55], v179 src0_sel:WORD_1
	v_pk_fma_f32 v[24:25], v[40:41], v[232:233], v[24:25] op_sel_hi:[1,0,1]
	v_pk_fma_f32 v[26:27], v[42:43], v[232:233], v[26:27] op_sel_hi:[1,0,1]
	v_pk_fma_f32 v[28:29], v[44:45], v[232:233], v[28:29] op_sel_hi:[1,0,1]
	v_pk_fma_f32 v[30:31], v[46:47], v[232:233], v[30:31] op_sel_hi:[1,0,1]
	v_pk_fma_f32 v[32:33], v[48:49], v[232:233], v[32:33] op_sel_hi:[1,0,1]
	v_pk_fma_f32 v[34:35], v[50:51], v[232:233], v[34:35] op_sel_hi:[1,0,1]
	v_pk_fma_f32 v[36:37], v[52:53], v[232:233], v[36:37] op_sel_hi:[1,0,1]
	v_pk_fma_f32 v[38:39], v[54:55], v[232:233], v[38:39] op_sel_hi:[1,0,1]
	v_cvt_pk_f32_fp8_e32 v[40:41], v180
	v_cvt_pk_f32_fp8_sdwa v[42:43], v180 src0_sel:WORD_1
	v_cvt_pk_f32_fp8_e32 v[44:45], v181
	v_cvt_pk_f32_fp8_sdwa v[46:47], v181 src0_sel:WORD_1
	v_cvt_pk_f32_fp8_e32 v[48:49], v182
	v_cvt_pk_f32_fp8_sdwa v[50:51], v182 src0_sel:WORD_1
	v_cvt_pk_f32_fp8_e32 v[52:53], v183
	v_cvt_pk_f32_fp8_sdwa v[54:55], v183 src0_sel:WORD_1
	v_pk_fma_f32 v[24:25], v[40:41], v[234:235], v[24:25] op_sel_hi:[1,0,1]
	v_pk_fma_f32 v[26:27], v[42:43], v[234:235], v[26:27] op_sel_hi:[1,0,1]
	v_pk_fma_f32 v[28:29], v[44:45], v[234:235], v[28:29] op_sel_hi:[1,0,1]
	v_pk_fma_f32 v[30:31], v[46:47], v[234:235], v[30:31] op_sel_hi:[1,0,1]
	v_pk_fma_f32 v[32:33], v[48:49], v[234:235], v[32:33] op_sel_hi:[1,0,1]
	v_pk_fma_f32 v[34:35], v[50:51], v[234:235], v[34:35] op_sel_hi:[1,0,1]
	v_pk_fma_f32 v[36:37], v[52:53], v[234:235], v[36:37] op_sel_hi:[1,0,1]
	v_pk_fma_f32 v[38:39], v[54:55], v[234:235], v[38:39] op_sel_hi:[1,0,1]
	v_cvt_pk_f32_fp8_e32 v[40:41], v184
	v_cvt_pk_f32_fp8_sdwa v[42:43], v184 src0_sel:WORD_1
	v_cvt_pk_f32_fp8_e32 v[44:45], v185
	v_cvt_pk_f32_fp8_sdwa v[46:47], v185 src0_sel:WORD_1
	v_cvt_pk_f32_fp8_e32 v[48:49], v186
	v_cvt_pk_f32_fp8_sdwa v[50:51], v186 src0_sel:WORD_1
	v_cvt_pk_f32_fp8_e32 v[52:53], v187
	v_cvt_pk_f32_fp8_sdwa v[54:55], v187 src0_sel:WORD_1
	v_pk_fma_f32 v[24:25], v[40:41], v[236:237], v[24:25] op_sel_hi:[1,0,1]
	v_pk_fma_f32 v[26:27], v[42:43], v[236:237], v[26:27] op_sel_hi:[1,0,1]
	v_pk_fma_f32 v[28:29], v[44:45], v[236:237], v[28:29] op_sel_hi:[1,0,1]
	v_pk_fma_f32 v[30:31], v[46:47], v[236:237], v[30:31] op_sel_hi:[1,0,1]
	v_pk_fma_f32 v[32:33], v[48:49], v[236:237], v[32:33] op_sel_hi:[1,0,1]
	v_pk_fma_f32 v[34:35], v[50:51], v[236:237], v[34:35] op_sel_hi:[1,0,1]
	v_pk_fma_f32 v[36:37], v[52:53], v[236:237], v[36:37] op_sel_hi:[1,0,1]
	v_pk_fma_f32 v[38:39], v[54:55], v[236:237], v[38:39] op_sel_hi:[1,0,1]
	v_cvt_pk_f32_fp8_e32 v[40:41], v188
	v_cvt_pk_f32_fp8_sdwa v[42:43], v188 src0_sel:WORD_1
	v_cvt_pk_f32_fp8_e32 v[44:45], v189
	v_cvt_pk_f32_fp8_sdwa v[46:47], v189 src0_sel:WORD_1
	v_cvt_pk_f32_fp8_e32 v[48:49], v190
	v_cvt_pk_f32_fp8_sdwa v[50:51], v190 src0_sel:WORD_1
	v_cvt_pk_f32_fp8_e32 v[52:53], v191
	v_cvt_pk_f32_fp8_sdwa v[54:55], v191 src0_sel:WORD_1
	v_pk_fma_f32 v[24:25], v[40:41], v[238:239], v[24:25] op_sel_hi:[1,0,1]
	v_pk_fma_f32 v[26:27], v[42:43], v[238:239], v[26:27] op_sel_hi:[1,0,1]
	v_pk_fma_f32 v[28:29], v[44:45], v[238:239], v[28:29] op_sel_hi:[1,0,1]
	v_pk_fma_f32 v[30:31], v[46:47], v[238:239], v[30:31] op_sel_hi:[1,0,1]
	v_pk_fma_f32 v[32:33], v[48:49], v[238:239], v[32:33] op_sel_hi:[1,0,1]
	v_pk_fma_f32 v[34:35], v[50:51], v[238:239], v[34:35] op_sel_hi:[1,0,1]
	v_pk_fma_f32 v[36:37], v[52:53], v[238:239], v[36:37] op_sel_hi:[1,0,1]
	v_pk_fma_f32 v[38:39], v[54:55], v[238:239], v[38:39] op_sel_hi:[1,0,1]
	ds_write_b128 v5, v[24:27]
	ds_write_b128 v5, v[28:31] offset:16
	ds_write_b128 v5, v[32:35] offset:32
	ds_write_b128 v5, v[36:39] offset:48
	ds_read_b64 v[40:41], v6
	ds_read_b64 v[42:43], v6 offset:512
	ds_read_b64 v[44:45], v6 offset:1024
	ds_read_b64 v[46:47], v6 offset:1536
	ds_read_b64 v[48:49], v6 offset:2048
	ds_read_b64 v[50:51], v6 offset:2560
	ds_read_b64 v[52:53], v6 offset:3072
	ds_read_b64 v[54:55], v6 offset:3584
	s_waitcnt lgkmcnt(6)
	v_pk_add_f32 v[40:41], v[40:41], v[42:43]
	s_waitcnt lgkmcnt(5)
	v_pk_add_f32 v[40:41], v[40:41], v[44:45]
	s_waitcnt lgkmcnt(4)
	v_pk_add_f32 v[40:41], v[40:41], v[46:47]
	s_waitcnt lgkmcnt(3)
	v_pk_add_f32 v[40:41], v[40:41], v[48:49]
	s_waitcnt lgkmcnt(2)
	v_pk_add_f32 v[40:41], v[40:41], v[50:51]
	s_waitcnt lgkmcnt(1)
	v_pk_add_f32 v[40:41], v[40:41], v[52:53]
	s_waitcnt lgkmcnt(0)
	v_pk_add_f32 v[40:41], v[40:41], v[54:55]
	v_pk_fma_f32 v[40:41], v[18:19], s[24:25], v[40:41] op_sel_hi:[1,0,1]
	s_lshl_b32 s30, s22, 12
	s_add_u32 s66, s16, s30
	s_addc_u32 s67, s17, 0
	global_store_dwordx2 v2, v[40:41], s[66:67]
	v_mov_b32_e32 v12, v14
	v_mov_b32_e32 v13, v15
	v_mov_b32_e32 v18, v20
	v_mov_b32_e32 v19, v21
	s_add_u32 s22, s22, s12
	s_cmp_ge_u32 s22, 0x8000
	s_cbranch_scc0 .Lgv_loop
